# attention: workgroup barriers moved from after each branch's accumulate to just before the next branch's accumulate (a whole iteration later)
# speedup vs baseline: 1.0287x; 1.0012x over previous
.Latt_unit:
	s_mov_b32 s33, s12
	s_mov_b32 s34, s15
	s_mov_b32 s35, s16
	s_mov_b32 s36, s17
	s_mov_b32 s38, s14
	s_mov_b32 s39, s13
	s_mov_b32 s24, s20
	s_mov_b32 s25, s21
	s_mov_b32 s26, s22
	s_mov_b32 s27, s23
	s_mov_b32 s40, s42
	s_mov_b32 s41, s43
	v_mov_b32_e32 v173, v176
	v_mov_b32_e32 v174, v177
	s_lshr_b32 s44, s33, 0
	s_lshr_b32 s2, s0, 2
	s_lshl_b32 s2, s2, 5
	s_lshr_b32 s3, s15, 2
	s_add_i32 s42, s3, s2
	s_and_b32 s43, s0, 3
	s_waitcnt vmcnt(4)
	ds_write_b128 v253, v[0:3]
	ds_write_b128 v253, v[4:7] offset:1152
	ds_write_b128 v253, v[8:11] offset:2304
	ds_write_b128 v253, v[12:15] offset:3456
	ds_write_b128 v253, v[16:19] offset:4608
	ds_write_b128 v253, v[20:23] offset:5760
	ds_write_b128 v253, v[24:27] offset:55296
	ds_write_b128 v253, v[28:31] offset:56448
	ds_write_b128 v253, v[32:35] offset:57600
	ds_write_b128 v253, v[36:39] offset:58752
	ds_write_b128 v253, v[40:43] offset:59904
	ds_write_b128 v253, v[44:47] offset:61056
	s_lshl_b32 s2, s0, 12
	s_add_i32 s2, s2, 0x1b500
	v_and_b32_e32 v141, 63, v145
	v_lshl_add_u32 v141, v141, 4, s2
	ds_write_b128 v141, v[48:51]
	ds_write_b128 v141, v[52:55] offset:1024
	ds_write_b128 v141, v[56:59] offset:2048
	ds_write_b128 v141, v[60:63] offset:3072
	s_waitcnt lgkmcnt(0)
	s_barrier
	v_add_u32_e32 v134, s42, v160
	v_lshlrev_b32_e32 v134, 2, v134
	v_add_u32_e32 v134, s43, v134
	v_subrev_u32_e32 v135, s15, v134
	v_lshrrev_b32_e32 v136, 4, v135
	v_add_u32_e32 v136, v136, v135
	v_mad_u32_u24 v176, v136, s79, v161
	v_lshl_add_u32 v177, v135, 2, s80
	s_lshl_b32 s2, s43, s13
	s_lshl_b32 s2, s2, 7
	s_add_u32 s86, s20, s2
	s_addc_u32 s87, s21, 0
	s_add_i32 s2, s42, -64
	v_add_u32_e32 v136, s2, v164
	v_ashrrev_i32_e32 v136, 2, v136
	v_med3_i32 v136, v136, 0, s14
	v_lshl_add_u32 v136, v136, 9, v178
	global_load_dwordx4 v[0:3], v136, s[86:87]
	s_add_i32 s2, s42, -56
	v_add_u32_e32 v135, s2, v164
	v_ashrrev_i32_e32 v135, 2, v135
	v_med3_i32 v135, v135, 0, s14
	v_lshl_add_u32 v135, v135, 9, v178
	global_load_dwordx4 v[4:7], v135, s[86:87]
	s_add_i32 s2, s42, -48
	v_add_u32_e32 v136, s2, v164
	v_ashrrev_i32_e32 v136, 2, v136
	v_med3_i32 v136, v136, 0, s14
	v_lshl_add_u32 v136, v136, 9, v178
	global_load_dwordx4 v[8:11], v136, s[86:87]
	s_add_i32 s2, s42, -40
	v_add_u32_e32 v135, s2, v164
	v_ashrrev_i32_e32 v135, 2, v135
	v_med3_i32 v135, v135, 0, s14
	v_lshl_add_u32 v135, v135, 9, v178
	global_load_dwordx4 v[12:15], v135, s[86:87]
	s_add_i32 s2, s42, -32
	v_add_u32_e32 v136, s2, v164
	v_ashrrev_i32_e32 v136, 2, v136
	v_med3_i32 v136, v136, 0, s14
	v_lshl_add_u32 v136, v136, 9, v178
	global_load_dwordx4 v[16:19], v136, s[86:87]
	s_add_i32 s2, s42, -24
	v_add_u32_e32 v135, s2, v164
	v_ashrrev_i32_e32 v135, 2, v135
	v_med3_i32 v135, v135, 0, s14
	v_lshl_add_u32 v135, v135, 9, v178
	global_load_dwordx4 v[20:23], v135, s[86:87]
	s_add_i32 s2, s42, -16
	v_add_u32_e32 v136, s2, v164
	v_ashrrev_i32_e32 v136, 2, v136
	v_med3_i32 v136, v136, 0, s14
	v_lshl_add_u32 v136, v136, 9, v178
	global_load_dwordx4 v[24:27], v136, s[86:87]
	s_add_i32 s2, s42, -8
	v_add_u32_e32 v135, s2, v164
	v_ashrrev_i32_e32 v135, 2, v135
	v_med3_i32 v135, v135, 0, s14
	v_lshl_add_u32 v135, v135, 9, v178
	global_load_dwordx4 v[28:31], v135, s[86:87]
	s_add_i32 s2, s42, 0
	v_add_u32_e32 v136, s2, v164
	v_ashrrev_i32_e32 v136, 2, v136
	v_med3_i32 v136, v136, 0, s14
	v_lshl_add_u32 v136, v136, 9, v178
	global_load_dwordx4 v[32:35], v136, s[86:87]
	s_add_i32 s2, s42, 8
	v_add_u32_e32 v135, s2, v164
	v_ashrrev_i32_e32 v135, 2, v135
	v_med3_i32 v135, v135, 0, s14
	v_lshl_add_u32 v135, v135, 9, v178
	global_load_dwordx4 v[36:39], v135, s[86:87]
	s_add_i32 s2, s42, 16
	v_add_u32_e32 v136, s2, v164
	v_ashrrev_i32_e32 v136, 2, v136
	v_med3_i32 v136, v136, 0, s14
	v_lshl_add_u32 v136, v136, 9, v178
	global_load_dwordx4 v[40:43], v136, s[86:87]
	s_add_i32 s2, s42, 24
	v_add_u32_e32 v135, s2, v164
	v_ashrrev_i32_e32 v135, 2, v135
	v_med3_i32 v135, v135, 0, s14
	v_lshl_add_u32 v135, v135, 9, v178
	global_load_dwordx4 v[44:47], v135, s[86:87]
	s_lshl_b32 s2, s43, s13
	s_lshl_b32 s2, s2, 7
	s_add_u32 s74, s22, s2
	s_addc_u32 s75, s23, 0
	s_add_i32 s2, s42, -64
	v_add_u32_e32 v137, s2, v164
	v_ashrrev_i32_e32 v137, 2, v137
	v_med3_i32 v137, v137, 0, s14
	v_lshl_add_u32 v137, v137, 9, v178
	global_load_dwordx4 v[64:67], v137, s[74:75]
	s_add_i32 s2, s42, -56
	v_add_u32_e32 v137, s2, v164
	v_ashrrev_i32_e32 v137, 2, v137
	v_med3_i32 v137, v137, 0, s14
	v_lshl_add_u32 v137, v137, 9, v178
	global_load_dwordx4 v[68:71], v137, s[74:75]
	s_add_i32 s2, s42, -48
	v_add_u32_e32 v137, s2, v164
	v_ashrrev_i32_e32 v137, 2, v137
	v_med3_i32 v137, v137, 0, s14
	v_lshl_add_u32 v137, v137, 9, v178
	global_load_dwordx4 v[72:75], v137, s[74:75]
	s_add_i32 s2, s42, -40
	v_add_u32_e32 v137, s2, v164
	v_ashrrev_i32_e32 v137, 2, v137
	v_med3_i32 v137, v137, 0, s14
	v_lshl_add_u32 v137, v137, 9, v178
	global_load_dwordx4 v[76:79], v137, s[74:75]
	s_lshl_b32 s2, s43, s13
	s_lshl_b32 s2, s2, 7
	s_add_u32 s74, s22, s2
	s_addc_u32 s75, s23, 0
	s_add_i32 s2, s42, -32
	v_add_u32_e32 v137, s2, v164
	v_ashrrev_i32_e32 v137, 2, v137
	v_med3_i32 v137, v137, 0, s14
	v_lshl_add_u32 v137, v137, 9, v178
	global_load_dwordx4 v[80:83], v137, s[74:75]
	s_add_i32 s2, s42, -24
	v_add_u32_e32 v137, s2, v164
	v_ashrrev_i32_e32 v137, 2, v137
	v_med3_i32 v137, v137, 0, s14
	v_lshl_add_u32 v137, v137, 9, v178
	global_load_dwordx4 v[84:87], v137, s[74:75]
	s_add_i32 s2, s42, -16
	v_add_u32_e32 v137, s2, v164
	v_ashrrev_i32_e32 v137, 2, v137
	v_med3_i32 v137, v137, 0, s14
	v_lshl_add_u32 v137, v137, 9, v178
	global_load_dwordx4 v[88:91], v137, s[74:75]
	s_add_i32 s2, s42, -8
	v_add_u32_e32 v137, s2, v164
	v_ashrrev_i32_e32 v137, 2, v137
	v_med3_i32 v137, v137, 0, s14
	v_lshl_add_u32 v137, v137, 9, v178
	global_load_dwordx4 v[92:95], v137, s[74:75]
	s_lshl_b32 s2, s43, s13
	s_lshl_b32 s2, s2, 7
	s_add_u32 s74, s22, s2
	s_addc_u32 s75, s23, 0
	s_add_i32 s2, s42, 0
	v_add_u32_e32 v137, s2, v164
	v_ashrrev_i32_e32 v137, 2, v137
	v_med3_i32 v137, v137, 0, s14
	v_lshl_add_u32 v137, v137, 9, v178
	global_load_dwordx4 v[96:99], v137, s[74:75]
	s_add_i32 s2, s42, 8
	v_add_u32_e32 v137, s2, v164
	v_ashrrev_i32_e32 v137, 2, v137
	v_med3_i32 v137, v137, 0, s14
	v_lshl_add_u32 v137, v137, 9, v178
	global_load_dwordx4 v[100:103], v137, s[74:75]
	s_add_i32 s2, s42, 16
	v_add_u32_e32 v137, s2, v164
	v_ashrrev_i32_e32 v137, 2, v137
	v_med3_i32 v137, v137, 0, s14
	v_lshl_add_u32 v137, v137, 9, v178
	global_load_dwordx4 v[104:107], v137, s[74:75]
	s_add_i32 s2, s42, 24
	v_add_u32_e32 v137, s2, v164
	v_ashrrev_i32_e32 v137, 2, v137
	v_med3_i32 v137, v137, 0, s14
	v_lshl_add_u32 v137, v137, 9, v178
	global_load_dwordx4 v[108:111], v137, s[74:75]
	v_subrev_u32_e32 v143, s80, v174
	v_lshl_add_u32 v143, v143, 5, v161
	v_add_u32_e32 v143, 0x1b500, v143
	ds_read_b128 v[48:51], v143
	ds_read_b128 v[52:55], v143 offset:64
	ds_read_b128 v[56:59], v143 offset:2048
	ds_read_b128 v[60:63], v143 offset:2112
	s_waitcnt lgkmcnt(0)
	v_mov_b32_e32 v138, 0
	v_mov_b32_e32 v139, 0
	v_mov_b32_e32 v140, 0
	v_mov_b32_e32 v141, 0
	ds_read_b128 v[204:207], v149
	ds_read_b128 v[208:211], v149 offset:64
	ds_read_b128 v[212:215], v149 offset:2304
	ds_read_b128 v[216:219], v149 offset:2368
	ds_read_b128 v[220:223], v149 offset:4608
	ds_read_b128 v[224:227], v149 offset:4672
	ds_read_b128 v[228:231], v149 offset:6912
	ds_read_b128 v[232:235], v149 offset:6976
	s_waitcnt lgkmcnt(0)
	v_mfma_f32_16x16x32_bf16 v[236:239], v[204:207], v[48:51], 0
	v_mfma_f32_16x16x32_bf16 v[236:239], v[208:211], v[52:55], v[236:239]
	v_mfma_f32_16x16x32_bf16 v[240:243], v[212:215], v[48:51], 0
	v_mfma_f32_16x16x32_bf16 v[240:243], v[216:219], v[52:55], v[240:243]
	v_mfma_f32_16x16x32_bf16 v[248:251], v[212:215], v[56:59], 0
	v_mfma_f32_16x16x32_bf16 v[248:251], v[216:219], v[60:63], v[248:251]
	s_nop 7
	s_add_i32 s77, s40, -64
	s_cmp_lt_u32 s77, s44
	s_cselect_b32 s76, s70, s71
	v_min_f32_e32 v152, s76, v236
	v_min_f32_e32 v153, s76, v237
	v_min_f32_e32 v154, s76, v238
	v_min_f32_e32 v155, s76, v239
	v_mfma_f32_16x16x32_bf16 v[236:239], v[220:223], v[48:51], 0
	v_mfma_f32_16x16x32_bf16 v[236:239], v[224:227], v[52:55], v[236:239]
	v_mfma_f32_16x16x32_bf16 v[244:247], v[220:223], v[56:59], 0
	v_mfma_f32_16x16x32_bf16 v[244:247], v[224:227], v[60:63], v[244:247]
	ds_read_b128 v[204:207], v149 offset:9216
	ds_read_b128 v[208:211], v149 offset:9280
	v_pk_mul_f32 v[152:153], v[152:153], s[72:73]
	v_pk_mul_f32 v[154:155], v[154:155], s[72:73]
	v_exp_f32_e32 v152, v152
	v_exp_f32_e32 v153, v153
	v_exp_f32_e32 v154, v154
	v_exp_f32_e32 v155, v155
	v_cndmask_b32_e64 v152, 0, v152, s[54:55]
	v_cndmask_b32_e64 v153, 0, v153, s[56:57]
	v_cndmask_b32_e64 v154, 0, v154, s[58:59]
	v_cndmask_b32_e64 v155, 0, v155, s[60:61]
	v_pk_add_f32 v[138:139], v[138:139], v[152:153]
	v_pk_add_f32 v[138:139], v[138:139], v[154:155]
	v_cvt_pk_bf16_f32 v112, v152, v153
	v_cvt_pk_bf16_f32 v113, v154, v155
	s_add_i32 s77, s40, -48
	s_cmp_lt_u32 s77, s44
	s_cselect_b32 s76, s70, s71
	v_min_f32_e32 v152, s76, v240
	v_min_f32_e32 v153, s76, v241
	v_min_f32_e32 v154, s76, v242
	v_min_f32_e32 v155, s76, v243
	v_min_f32_e32 v156, s76, v248
	v_min_f32_e32 v157, s76, v249
	v_min_f32_e32 v158, s76, v250
	v_min_f32_e32 v159, s76, v251
	v_mfma_f32_16x16x32_bf16 v[240:243], v[228:231], v[48:51], 0
	v_mfma_f32_16x16x32_bf16 v[240:243], v[232:235], v[52:55], v[240:243]
	v_mfma_f32_16x16x32_bf16 v[248:251], v[228:231], v[56:59], 0
	v_mfma_f32_16x16x32_bf16 v[248:251], v[232:235], v[60:63], v[248:251]
	ds_read_b128 v[212:215], v149 offset:11520
	ds_read_b128 v[216:219], v149 offset:11584
	v_pk_mul_f32 v[152:153], v[152:153], s[72:73]
	v_pk_mul_f32 v[154:155], v[154:155], s[72:73]
	v_exp_f32_e32 v152, v152
	v_exp_f32_e32 v153, v153
	v_exp_f32_e32 v154, v154
	v_exp_f32_e32 v155, v155
	v_pk_add_f32 v[138:139], v[138:139], v[152:153]
	v_pk_add_f32 v[138:139], v[138:139], v[154:155]
	v_cvt_pk_bf16_f32 v114, v152, v153
	v_cvt_pk_bf16_f32 v115, v154, v155
	v_pk_mul_f32 v[156:157], v[156:157], s[72:73]
	v_pk_mul_f32 v[158:159], v[158:159], s[72:73]
	v_exp_f32_e32 v156, v156
	v_exp_f32_e32 v157, v157
	v_exp_f32_e32 v158, v158
	v_exp_f32_e32 v159, v159
	v_cndmask_b32_e64 v156, 0, v156, s[54:55]
	v_cndmask_b32_e64 v157, 0, v157, s[56:57]
	v_cndmask_b32_e64 v158, 0, v158, s[58:59]
	v_cndmask_b32_e64 v159, 0, v159, s[60:61]
	v_pk_add_f32 v[140:141], v[140:141], v[156:157]
	v_pk_add_f32 v[140:141], v[140:141], v[158:159]
	v_cvt_pk_bf16_f32 v186, v156, v157
	v_cvt_pk_bf16_f32 v187, v158, v159
	s_add_i32 s77, s40, -32
	s_cmp_lt_u32 s77, s44
	s_cselect_b32 s76, s70, s71
	v_min_f32_e32 v152, s76, v236
	v_min_f32_e32 v153, s76, v237
	v_min_f32_e32 v154, s76, v238
	v_min_f32_e32 v155, s76, v239
	v_min_f32_e32 v156, s76, v244
	v_min_f32_e32 v157, s76, v245
	v_min_f32_e32 v158, s76, v246
	v_min_f32_e32 v159, s76, v247
	s_waitcnt lgkmcnt(2)
	v_mfma_f32_16x16x32_bf16 v[236:239], v[204:207], v[48:51], 0
	v_mfma_f32_16x16x32_bf16 v[236:239], v[208:211], v[52:55], v[236:239]
	v_mfma_f32_16x16x32_bf16 v[244:247], v[204:207], v[56:59], 0
	v_mfma_f32_16x16x32_bf16 v[244:247], v[208:211], v[60:63], v[244:247]
	ds_read_b128 v[220:223], v149 offset:13824
	ds_read_b128 v[224:227], v149 offset:13888
	v_pk_mul_f32 v[152:153], v[152:153], s[72:73]
	v_pk_mul_f32 v[154:155], v[154:155], s[72:73]
	v_exp_f32_e32 v152, v152
	v_exp_f32_e32 v153, v153
	v_exp_f32_e32 v154, v154
	v_exp_f32_e32 v155, v155
	v_pk_add_f32 v[138:139], v[138:139], v[152:153]
	v_pk_add_f32 v[138:139], v[138:139], v[154:155]
	v_cvt_pk_bf16_f32 v116, v152, v153
	v_cvt_pk_bf16_f32 v117, v154, v155
	v_pk_mul_f32 v[156:157], v[156:157], s[72:73]
	v_pk_mul_f32 v[158:159], v[158:159], s[72:73]
	v_exp_f32_e32 v156, v156
	v_exp_f32_e32 v157, v157
	v_exp_f32_e32 v158, v158
	v_exp_f32_e32 v159, v159
	v_pk_add_f32 v[140:141], v[140:141], v[156:157]
	v_pk_add_f32 v[140:141], v[140:141], v[158:159]
	v_cvt_pk_bf16_f32 v188, v156, v157
	v_cvt_pk_bf16_f32 v189, v158, v159
	s_add_i32 s77, s40, -16
	s_cmp_lt_u32 s77, s44
	s_cselect_b32 s76, s70, s71
	v_min_f32_e32 v152, s76, v240
	v_min_f32_e32 v153, s76, v241
	v_min_f32_e32 v154, s76, v242
	v_min_f32_e32 v155, s76, v243
	v_min_f32_e32 v156, s76, v248
	v_min_f32_e32 v157, s76, v249
	v_min_f32_e32 v158, s76, v250
	v_min_f32_e32 v159, s76, v251
	s_waitcnt lgkmcnt(2)
	v_mfma_f32_16x16x32_bf16 v[240:243], v[212:215], v[48:51], 0
	v_mfma_f32_16x16x32_bf16 v[240:243], v[216:219], v[52:55], v[240:243]
	v_mfma_f32_16x16x32_bf16 v[248:251], v[212:215], v[56:59], 0
	v_mfma_f32_16x16x32_bf16 v[248:251], v[216:219], v[60:63], v[248:251]
	ds_read_b128 v[228:231], v149 offset:16128
	ds_read_b128 v[232:235], v149 offset:16192
	v_pk_mul_f32 v[152:153], v[152:153], s[72:73]
	v_pk_mul_f32 v[154:155], v[154:155], s[72:73]
	v_exp_f32_e32 v152, v152
	v_exp_f32_e32 v153, v153
	v_exp_f32_e32 v154, v154
	v_exp_f32_e32 v155, v155
	v_pk_add_f32 v[138:139], v[138:139], v[152:153]
	v_pk_add_f32 v[138:139], v[138:139], v[154:155]
	v_cvt_pk_bf16_f32 v118, v152, v153
	v_cvt_pk_bf16_f32 v119, v154, v155
	v_pk_mul_f32 v[156:157], v[156:157], s[72:73]
	v_pk_mul_f32 v[158:159], v[158:159], s[72:73]
	v_exp_f32_e32 v156, v156
	v_exp_f32_e32 v157, v157
	v_exp_f32_e32 v158, v158
	v_exp_f32_e32 v159, v159
	v_pk_add_f32 v[140:141], v[140:141], v[156:157]
	v_pk_add_f32 v[140:141], v[140:141], v[158:159]
	v_cvt_pk_bf16_f32 v190, v156, v157
	v_cvt_pk_bf16_f32 v191, v158, v159
	s_add_i32 s77, s40, 0
	s_cmp_lt_u32 s77, s44
	s_cselect_b32 s76, s70, s71
	v_min_f32_e32 v152, s76, v236
	v_min_f32_e32 v153, s76, v237
	v_min_f32_e32 v154, s76, v238
	v_min_f32_e32 v155, s76, v239
	v_min_f32_e32 v156, s76, v244
	v_min_f32_e32 v157, s76, v245
	v_min_f32_e32 v158, s76, v246
	v_min_f32_e32 v159, s76, v247
	s_waitcnt lgkmcnt(2)
	v_mfma_f32_16x16x32_bf16 v[236:239], v[220:223], v[48:51], 0
	v_mfma_f32_16x16x32_bf16 v[236:239], v[224:227], v[52:55], v[236:239]
	v_mfma_f32_16x16x32_bf16 v[244:247], v[220:223], v[56:59], 0
	v_mfma_f32_16x16x32_bf16 v[244:247], v[224:227], v[60:63], v[244:247]
	ds_read_b128 v[204:207], v149 offset:18432
	ds_read_b128 v[208:211], v149 offset:18496
	v_pk_mul_f32 v[152:153], v[152:153], s[72:73]
	v_pk_mul_f32 v[154:155], v[154:155], s[72:73]
	v_exp_f32_e32 v152, v152
	v_exp_f32_e32 v153, v153
	v_exp_f32_e32 v154, v154
	v_exp_f32_e32 v155, v155
	v_pk_add_f32 v[138:139], v[138:139], v[152:153]
	v_pk_add_f32 v[138:139], v[138:139], v[154:155]
	v_cvt_pk_bf16_f32 v120, v152, v153
	v_cvt_pk_bf16_f32 v121, v154, v155
	v_pk_mul_f32 v[156:157], v[156:157], s[72:73]
	v_pk_mul_f32 v[158:159], v[158:159], s[72:73]
	v_exp_f32_e32 v156, v156
	v_exp_f32_e32 v157, v157
	v_exp_f32_e32 v158, v158
	v_exp_f32_e32 v159, v159
	v_pk_add_f32 v[140:141], v[140:141], v[156:157]
	v_pk_add_f32 v[140:141], v[140:141], v[158:159]
	v_cvt_pk_bf16_f32 v192, v156, v157
	v_cvt_pk_bf16_f32 v193, v158, v159
	s_add_i32 s77, s40, 16
	s_cmp_lt_u32 s77, s44
	s_cselect_b32 s76, s70, s71
	v_min_f32_e32 v152, s76, v240
	v_min_f32_e32 v153, s76, v241
	v_min_f32_e32 v154, s76, v242
	v_min_f32_e32 v155, s76, v243
	v_min_f32_e32 v156, s76, v248
	v_min_f32_e32 v157, s76, v249
	v_min_f32_e32 v158, s76, v250
	v_min_f32_e32 v159, s76, v251
	s_waitcnt lgkmcnt(2)
	v_mfma_f32_16x16x32_bf16 v[240:243], v[228:231], v[48:51], 0
	v_mfma_f32_16x16x32_bf16 v[240:243], v[232:235], v[52:55], v[240:243]
	v_mfma_f32_16x16x32_bf16 v[248:251], v[228:231], v[56:59], 0
	v_mfma_f32_16x16x32_bf16 v[248:251], v[232:235], v[60:63], v[248:251]
	ds_read_b128 v[212:215], v149 offset:20736
	ds_read_b128 v[216:219], v149 offset:20800
	v_pk_mul_f32 v[152:153], v[152:153], s[72:73]
	v_pk_mul_f32 v[154:155], v[154:155], s[72:73]
	v_exp_f32_e32 v152, v152
	v_exp_f32_e32 v153, v153
	v_exp_f32_e32 v154, v154
	v_exp_f32_e32 v155, v155
	v_pk_add_f32 v[138:139], v[138:139], v[152:153]
	v_pk_add_f32 v[138:139], v[138:139], v[154:155]
	v_cvt_pk_bf16_f32 v122, v152, v153
	v_cvt_pk_bf16_f32 v123, v154, v155
	v_pk_mul_f32 v[156:157], v[156:157], s[72:73]
	v_pk_mul_f32 v[158:159], v[158:159], s[72:73]
	v_exp_f32_e32 v156, v156
	v_exp_f32_e32 v157, v157
	v_exp_f32_e32 v158, v158
	v_exp_f32_e32 v159, v159
	v_pk_add_f32 v[140:141], v[140:141], v[156:157]
	v_pk_add_f32 v[140:141], v[140:141], v[158:159]
	v_cvt_pk_bf16_f32 v194, v156, v157
	v_cvt_pk_bf16_f32 v195, v158, v159
	s_add_i32 s77, s40, 32
	s_cmp_lt_u32 s77, s44
	s_cselect_b32 s76, s70, s71
	v_min_f32_e32 v152, s76, v236
	v_min_f32_e32 v153, s76, v237
	v_min_f32_e32 v154, s76, v238
	v_min_f32_e32 v155, s76, v239
	v_min_f32_e32 v156, s76, v244
	v_min_f32_e32 v157, s76, v245
	v_min_f32_e32 v158, s76, v246
	v_min_f32_e32 v159, s76, v247
	s_waitcnt lgkmcnt(2)
	v_mfma_f32_16x16x32_bf16 v[236:239], v[204:207], v[48:51], 0
	v_mfma_f32_16x16x32_bf16 v[236:239], v[208:211], v[52:55], v[236:239]
	v_mfma_f32_16x16x32_bf16 v[244:247], v[204:207], v[56:59], 0
	v_mfma_f32_16x16x32_bf16 v[244:247], v[208:211], v[60:63], v[244:247]
	v_pk_mul_f32 v[152:153], v[152:153], s[72:73]
	v_pk_mul_f32 v[154:155], v[154:155], s[72:73]
	v_exp_f32_e32 v152, v152
	v_exp_f32_e32 v153, v153
	v_exp_f32_e32 v154, v154
	v_exp_f32_e32 v155, v155
	v_pk_add_f32 v[138:139], v[138:139], v[152:153]
	v_pk_add_f32 v[138:139], v[138:139], v[154:155]
	v_cvt_pk_bf16_f32 v124, v152, v153
	v_cvt_pk_bf16_f32 v125, v154, v155
	v_pk_mul_f32 v[156:157], v[156:157], s[72:73]
	v_pk_mul_f32 v[158:159], v[158:159], s[72:73]
	v_exp_f32_e32 v156, v156
	v_exp_f32_e32 v157, v157
	v_exp_f32_e32 v158, v158
	v_exp_f32_e32 v159, v159
	v_pk_add_f32 v[140:141], v[140:141], v[156:157]
	v_pk_add_f32 v[140:141], v[140:141], v[158:159]
	v_cvt_pk_bf16_f32 v196, v156, v157
	v_cvt_pk_bf16_f32 v197, v158, v159
	s_add_i32 s77, s40, 48
	s_cmp_lt_u32 s77, s44
	s_cselect_b32 s76, s70, s71
	v_min_f32_e32 v152, s76, v240
	v_min_f32_e32 v153, s76, v241
	v_min_f32_e32 v154, s76, v242
	v_min_f32_e32 v155, s76, v243
	v_min_f32_e32 v156, s76, v248
	v_min_f32_e32 v157, s76, v249
	v_min_f32_e32 v158, s76, v250
	v_min_f32_e32 v159, s76, v251
	s_waitcnt lgkmcnt(0)
	v_mfma_f32_16x16x32_bf16 v[248:251], v[212:215], v[56:59], 0
	v_mfma_f32_16x16x32_bf16 v[248:251], v[216:219], v[60:63], v[248:251]
	v_pk_mul_f32 v[152:153], v[152:153], s[72:73]
	v_pk_mul_f32 v[154:155], v[154:155], s[72:73]
	v_exp_f32_e32 v152, v152
	v_exp_f32_e32 v153, v153
	v_exp_f32_e32 v154, v154
	v_exp_f32_e32 v155, v155
	v_pk_add_f32 v[138:139], v[138:139], v[152:153]
	v_pk_add_f32 v[138:139], v[138:139], v[154:155]
	v_cvt_pk_bf16_f32 v126, v152, v153
	v_cvt_pk_bf16_f32 v127, v154, v155
	v_pk_mul_f32 v[156:157], v[156:157], s[72:73]
	v_pk_mul_f32 v[158:159], v[158:159], s[72:73]
	v_exp_f32_e32 v156, v156
	v_exp_f32_e32 v157, v157
	v_exp_f32_e32 v158, v158
	v_exp_f32_e32 v159, v159
	v_pk_add_f32 v[140:141], v[140:141], v[156:157]
	v_pk_add_f32 v[140:141], v[140:141], v[158:159]
	v_cvt_pk_bf16_f32 v198, v156, v157
	v_cvt_pk_bf16_f32 v199, v158, v159
	s_add_i32 s77, s40, 64
	s_cmp_lt_u32 s77, s44
	s_cselect_b32 s76, s70, s71
	v_min_f32_e32 v152, s76, v236
	v_min_f32_e32 v153, s76, v237
	v_min_f32_e32 v154, s76, v238
	v_min_f32_e32 v155, s76, v239
	v_min_f32_e32 v156, s76, v244
	v_min_f32_e32 v157, s76, v245
	v_min_f32_e32 v158, s76, v246
	v_min_f32_e32 v159, s76, v247
	v_pk_mul_f32 v[152:153], v[152:153], s[72:73]
	v_pk_mul_f32 v[154:155], v[154:155], s[72:73]
	v_exp_f32_e32 v152, v152
	v_exp_f32_e32 v153, v153
	v_exp_f32_e32 v154, v154
	v_exp_f32_e32 v155, v155
	v_cndmask_b32_e64 v152, 0, v152, s[62:63]
	v_cndmask_b32_e64 v153, 0, v153, s[64:65]
	v_cndmask_b32_e64 v154, 0, v154, s[66:67]
	v_cndmask_b32_e64 v155, 0, v155, s[68:69]
	v_pk_add_f32 v[138:139], v[138:139], v[152:153]
	v_pk_add_f32 v[138:139], v[138:139], v[154:155]
	v_cvt_pk_bf16_f32 v128, v152, v153
	v_cvt_pk_bf16_f32 v129, v154, v155
	v_pk_mul_f32 v[156:157], v[156:157], s[72:73]
	v_pk_mul_f32 v[158:159], v[158:159], s[72:73]
	v_exp_f32_e32 v156, v156
	v_exp_f32_e32 v157, v157
	v_exp_f32_e32 v158, v158
	v_exp_f32_e32 v159, v159
	v_pk_add_f32 v[140:141], v[140:141], v[156:157]
	v_pk_add_f32 v[140:141], v[140:141], v[158:159]
	v_cvt_pk_bf16_f32 v200, v156, v157
	v_cvt_pk_bf16_f32 v201, v158, v159
	s_add_i32 s77, s40, 80
	s_cmp_lt_u32 s77, s44
	s_cselect_b32 s76, s70, s71
	v_min_f32_e32 v156, s76, v248
	v_min_f32_e32 v157, s76, v249
	v_min_f32_e32 v158, s76, v250
	v_min_f32_e32 v159, s76, v251
	v_pk_mul_f32 v[156:157], v[156:157], s[72:73]
	v_pk_mul_f32 v[158:159], v[158:159], s[72:73]
	v_exp_f32_e32 v156, v156
	v_exp_f32_e32 v157, v157
	v_exp_f32_e32 v158, v158
	v_exp_f32_e32 v159, v159
	v_cndmask_b32_e64 v156, 0, v156, s[62:63]
	v_cndmask_b32_e64 v157, 0, v157, s[64:65]
	v_cndmask_b32_e64 v158, 0, v158, s[66:67]
	v_cndmask_b32_e64 v159, 0, v159, s[68:69]
	v_pk_add_f32 v[140:141], v[140:141], v[156:157]
	v_pk_add_f32 v[140:141], v[140:141], v[158:159]
	v_cvt_pk_bf16_f32 v202, v156, v157
	v_cvt_pk_bf16_f32 v203, v158, v159
	v_add_f32_e32 v132, v138, v139
	v_add_f32_e32 v133, v140, v141
	ds_bpermute_b32 v142, v167, v132
	ds_bpermute_b32 v143, v167, v133
	ds_read_b64_tr_b16 v[236:237], v151 offset:0
	ds_read_b64_tr_b16 v[238:239], v151 offset:2304
	ds_read_b64_tr_b16 v[240:241], v151 offset:32
	ds_read_b64_tr_b16 v[242:243], v151 offset:2336
	ds_read_b64_tr_b16 v[244:245], v151 offset:64
	ds_read_b64_tr_b16 v[246:247], v151 offset:2368
	ds_read_b64_tr_b16 v[248:249], v151 offset:96
	ds_read_b64_tr_b16 v[250:251], v151 offset:2400
	s_waitcnt lgkmcnt(0)
	v_add_f32_e32 v132, v132, v142
	v_add_f32_e32 v133, v133, v143
	ds_bpermute_b32 v142, v168, v132
	ds_bpermute_b32 v143, v168, v133
	ds_read_b64_tr_b16 v[48:49], v151 offset:4608
	ds_read_b64_tr_b16 v[50:51], v151 offset:6912
	ds_read_b64_tr_b16 v[52:53], v151 offset:4640
	ds_read_b64_tr_b16 v[54:55], v151 offset:6944
	ds_read_b64_tr_b16 v[56:57], v151 offset:4672
	ds_read_b64_tr_b16 v[58:59], v151 offset:6976
	ds_read_b64_tr_b16 v[60:61], v151 offset:4704
	ds_read_b64_tr_b16 v[62:63], v151 offset:7008
	v_mfma_f32_16x16x32_bf16 v[204:207], v[236:239], v[112:115], 0
	v_mfma_f32_16x16x32_bf16 v[208:211], v[240:243], v[112:115], 0
	v_mfma_f32_16x16x32_bf16 v[212:215], v[244:247], v[112:115], 0
	v_mfma_f32_16x16x32_bf16 v[216:219], v[248:251], v[112:115], 0
	v_mfma_f32_16x16x32_bf16 v[220:223], v[236:239], v[184:187], 0
	v_mfma_f32_16x16x32_bf16 v[224:227], v[240:243], v[184:187], 0
	v_mfma_f32_16x16x32_bf16 v[228:231], v[244:247], v[184:187], 0
	v_mfma_f32_16x16x32_bf16 v[232:235], v[248:251], v[184:187], 0
	s_waitcnt lgkmcnt(0)
	v_add_f32_e32 v132, v132, v142
	v_add_f32_e32 v133, v133, v143
	ds_read_b64_tr_b16 v[236:237], v151 offset:9216
	ds_read_b64_tr_b16 v[238:239], v151 offset:11520
	ds_read_b64_tr_b16 v[240:241], v151 offset:9248
	ds_read_b64_tr_b16 v[242:243], v151 offset:11552
	ds_read_b64_tr_b16 v[244:245], v151 offset:9280
	ds_read_b64_tr_b16 v[246:247], v151 offset:11584
	ds_read_b64_tr_b16 v[248:249], v151 offset:9312
	ds_read_b64_tr_b16 v[250:251], v151 offset:11616
	v_mfma_f32_16x16x32_bf16 v[204:207], v[48:51], v[116:119], v[204:207]
	v_mfma_f32_16x16x32_bf16 v[208:211], v[52:55], v[116:119], v[208:211]
	v_mfma_f32_16x16x32_bf16 v[212:215], v[56:59], v[116:119], v[212:215]
	v_mfma_f32_16x16x32_bf16 v[216:219], v[60:63], v[116:119], v[216:219]
	v_mfma_f32_16x16x32_bf16 v[220:223], v[48:51], v[188:191], v[220:223]
	v_mfma_f32_16x16x32_bf16 v[224:227], v[52:55], v[188:191], v[224:227]
	v_mfma_f32_16x16x32_bf16 v[228:231], v[56:59], v[188:191], v[228:231]
	v_mfma_f32_16x16x32_bf16 v[232:235], v[60:63], v[188:191], v[232:235]
	s_waitcnt lgkmcnt(0)
	ds_read_b64_tr_b16 v[48:49], v151 offset:13824
	ds_read_b64_tr_b16 v[50:51], v151 offset:16128
	ds_read_b64_tr_b16 v[52:53], v151 offset:13856
	ds_read_b64_tr_b16 v[54:55], v151 offset:16160
	ds_read_b64_tr_b16 v[56:57], v151 offset:13888
	ds_read_b64_tr_b16 v[58:59], v151 offset:16192
	ds_read_b64_tr_b16 v[60:61], v151 offset:13920
	ds_read_b64_tr_b16 v[62:63], v151 offset:16224
	v_mfma_f32_16x16x32_bf16 v[204:207], v[236:239], v[120:123], v[204:207]
	v_mfma_f32_16x16x32_bf16 v[208:211], v[240:243], v[120:123], v[208:211]
	v_mfma_f32_16x16x32_bf16 v[212:215], v[244:247], v[120:123], v[212:215]
	v_mfma_f32_16x16x32_bf16 v[216:219], v[248:251], v[120:123], v[216:219]
	v_mfma_f32_16x16x32_bf16 v[220:223], v[236:239], v[192:195], v[220:223]
	v_mfma_f32_16x16x32_bf16 v[224:227], v[240:243], v[192:195], v[224:227]
	v_mfma_f32_16x16x32_bf16 v[228:231], v[244:247], v[192:195], v[228:231]
	v_mfma_f32_16x16x32_bf16 v[232:235], v[248:251], v[192:195], v[232:235]
	s_waitcnt lgkmcnt(0)
	ds_read_b64_tr_b16 v[236:237], v151 offset:18432
	ds_read_b64_tr_b16 v[238:239], v151 offset:20736
	ds_read_b64_tr_b16 v[240:241], v151 offset:18464
	ds_read_b64_tr_b16 v[242:243], v151 offset:20768
	ds_read_b64_tr_b16 v[244:245], v151 offset:18496
	ds_read_b64_tr_b16 v[246:247], v151 offset:20800
	ds_read_b64_tr_b16 v[248:249], v151 offset:18528
	ds_read_b64_tr_b16 v[250:251], v151 offset:20832
	v_mfma_f32_16x16x32_bf16 v[204:207], v[48:51], v[124:127], v[204:207]
	v_mfma_f32_16x16x32_bf16 v[208:211], v[52:55], v[124:127], v[208:211]
	v_mfma_f32_16x16x32_bf16 v[212:215], v[56:59], v[124:127], v[212:215]
	v_mfma_f32_16x16x32_bf16 v[216:219], v[60:63], v[124:127], v[216:219]
	v_mfma_f32_16x16x32_bf16 v[220:223], v[48:51], v[196:199], v[220:223]
	v_mfma_f32_16x16x32_bf16 v[224:227], v[52:55], v[196:199], v[224:227]
	v_mfma_f32_16x16x32_bf16 v[228:231], v[56:59], v[196:199], v[228:231]
	v_mfma_f32_16x16x32_bf16 v[232:235], v[60:63], v[196:199], v[232:235]
	s_waitcnt lgkmcnt(0)
	v_mfma_f32_16x16x32_bf16 v[204:207], v[236:239], v[128:131], v[204:207]
	v_mfma_f32_16x16x32_bf16 v[208:211], v[240:243], v[128:131], v[208:211]
	v_mfma_f32_16x16x32_bf16 v[212:215], v[244:247], v[128:131], v[212:215]
	v_mfma_f32_16x16x32_bf16 v[216:219], v[248:251], v[128:131], v[216:219]
	v_mfma_f32_16x16x32_bf16 v[220:223], v[236:239], v[200:203], v[220:223]
	v_mfma_f32_16x16x32_bf16 v[224:227], v[240:243], v[200:203], v[224:227]
	v_mfma_f32_16x16x32_bf16 v[228:231], v[244:247], v[200:203], v[228:231]
	v_mfma_f32_16x16x32_bf16 v[232:235], v[248:251], v[200:203], v[232:235]
	s_barrier
	s_add_i32 s2, s42, 32
	v_add_u32_e32 v136, s2, v164
	v_ashrrev_i32_e32 v136, 2, v136
	v_med3_i32 v136, v136, 0, s14
	v_lshl_add_u32 v136, v136, 9, v178
	global_load_dwordx4 v[120:123], v136, s[86:87]
	s_add_i32 s2, s42, 40
	v_add_u32_e32 v135, s2, v164
	v_ashrrev_i32_e32 v135, 2, v135
	v_med3_i32 v135, v135, 0, s14
	v_lshl_add_u32 v135, v135, 9, v178
	global_load_dwordx4 v[124:127], v135, s[86:87]
	s_add_i32 s2, s42, 48
	v_add_u32_e32 v136, s2, v164
	v_ashrrev_i32_e32 v136, 2, v136
	v_med3_i32 v136, v136, 0, s14
	v_lshl_add_u32 v136, v136, 9, v178
	global_load_dwordx4 v[192:195], v136, s[86:87]
	s_add_i32 s2, s42, 56
	v_add_u32_e32 v135, s2, v164
	v_ashrrev_i32_e32 v135, 2, v135
	v_med3_i32 v135, v135, 0, s14
	v_lshl_add_u32 v135, v135, 9, v178
	global_load_dwordx4 v[196:199], v135, s[86:87]
	ds_write_b128 v173, v[204:207] offset:0
	ds_write_b128 v173, v[208:211] offset:64
	ds_write_b128 v173, v[212:215] offset:128
	ds_write_b128 v173, v[216:219] offset:192
	ds_write_b32 v174, v132 offset:0
	ds_write_b128 v173, v[220:223] offset:4624
	ds_write_b128 v173, v[224:227] offset:4688
	ds_write_b128 v173, v[228:231] offset:4752
	ds_write_b128 v173, v[232:235] offset:4816
	ds_write_b32 v174, v133 offset:64
	s_mov_b32 s40, s42
	s_mov_b32 s41, s43
	v_mov_b32_e32 v173, v176
	v_mov_b32_e32 v174, v177
	s_lshr_b32 s44, s33, 2
	s_lshr_b32 s42, s15, 4
	s_add_i32 s43, s0, 0
	v_subrev_u32_e32 v143, s80, v174
	v_lshl_add_u32 v143, v143, 5, v161
	v_add_u32_e32 v143, 0x1b500, v143
	ds_read_b128 v[48:51], v143
	ds_read_b128 v[52:55], v143 offset:64
	ds_read_b128 v[56:59], v143 offset:8192
	ds_read_b128 v[60:63], v143 offset:8256
	s_waitcnt lgkmcnt(0)
	v_mov_b32_e32 v138, 0
	v_mov_b32_e32 v139, 0
	v_mov_b32_e32 v140, 0
	v_mov_b32_e32 v141, 0
	s_waitcnt vmcnt(24)
	ds_write_b128 v165, v[0:3]
	ds_write_b128 v165, v[4:7] offset:1152
	ds_write_b128 v165, v[8:11] offset:2304
	ds_write_b128 v165, v[12:15] offset:3456
	s_waitcnt lgkmcnt(0)
	ds_read_b128 v[204:207], v175
	ds_read_b128 v[208:211], v175 offset:64
	ds_read_b128 v[212:215], v175 offset:2304
	ds_read_b128 v[216:219], v175 offset:2368
	s_lshl_b32 s2, s41, s39
	s_lshl_b32 s2, s2, 7
	s_add_u32 s86, s24, s2
	s_addc_u32 s87, s25, 0
	s_add_i32 s2, s40, 64
	v_add_u32_e32 v136, s2, v164
	v_ashrrev_i32_e32 v136, 2, v136
	v_med3_i32 v136, v136, 0, s38
	v_lshl_add_u32 v136, v136, 9, v178
	global_load_dwordx4 v[0:3], v136, s[86:87]
	s_add_i32 s2, s40, 72
	v_add_u32_e32 v135, s2, v164
	v_ashrrev_i32_e32 v135, 2, v135
	v_med3_i32 v135, v135, 0, s38
	v_lshl_add_u32 v135, v135, 9, v178
	global_load_dwordx4 v[4:7], v135, s[86:87]
	s_add_i32 s2, s40, 80
	v_add_u32_e32 v136, s2, v164
	v_ashrrev_i32_e32 v136, 2, v136
	v_med3_i32 v136, v136, 0, s38
	v_lshl_add_u32 v136, v136, 9, v178
	global_load_dwordx4 v[8:11], v136, s[86:87]
	s_add_i32 s2, s40, 88
	v_add_u32_e32 v135, s2, v164
	v_ashrrev_i32_e32 v135, 2, v135
	v_med3_i32 v135, v135, 0, s38
	v_lshl_add_u32 v135, v135, 9, v178
	global_load_dwordx4 v[12:15], v135, s[86:87]
	s_waitcnt vmcnt(24)
	s_waitcnt lgkmcnt(0)
	ds_write_b128 v165, v[16:19]
	ds_write_b128 v165, v[20:23] offset:1152
	ds_write_b128 v165, v[24:27] offset:2304
	ds_write_b128 v165, v[28:31] offset:3456
	v_mfma_f32_16x16x32_bf16 v[236:239], v[204:207], v[48:51], 0
	v_mfma_f32_16x16x32_bf16 v[236:239], v[208:211], v[52:55], v[236:239]
	v_mfma_f32_16x16x32_bf16 v[240:243], v[212:215], v[48:51], 0
	v_mfma_f32_16x16x32_bf16 v[240:243], v[216:219], v[52:55], v[240:243]
	v_mfma_f32_16x16x32_bf16 v[248:251], v[212:215], v[56:59], 0
	v_mfma_f32_16x16x32_bf16 v[248:251], v[216:219], v[60:63], v[248:251]
	s_waitcnt lgkmcnt(0)
	ds_read_b128 v[220:223], v175
	ds_read_b128 v[224:227], v175 offset:64
	s_lshl_b32 s2, s41, s39
	s_lshl_b32 s2, s2, 7
	s_add_u32 s74, s26, s2
	s_addc_u32 s75, s27, 0
	s_add_i32 s2, s40, 32
	v_add_u32_e32 v137, s2, v164
	v_ashrrev_i32_e32 v137, 2, v137
	v_med3_i32 v137, v137, 0, s38
	v_lshl_add_u32 v137, v137, 9, v178
	global_load_dwordx4 v[16:19], v137, s[74:75]
	s_add_i32 s2, s40, 40
	v_add_u32_e32 v137, s2, v164
	v_ashrrev_i32_e32 v137, 2, v137
	v_med3_i32 v137, v137, 0, s38
	v_lshl_add_u32 v137, v137, 9, v178
	global_load_dwordx4 v[20:23], v137, s[74:75]
	s_add_i32 s2, s40, 48
	v_add_u32_e32 v137, s2, v164
	v_ashrrev_i32_e32 v137, 2, v137
	v_med3_i32 v137, v137, 0, s38
	v_lshl_add_u32 v137, v137, 9, v178
	global_load_dwordx4 v[24:27], v137, s[74:75]
	s_add_i32 s2, s40, 56
	v_add_u32_e32 v137, s2, v164
	v_ashrrev_i32_e32 v137, 2, v137
	v_med3_i32 v137, v137, 0, s38
	v_lshl_add_u32 v137, v137, 9, v178
	global_load_dwordx4 v[28:31], v137, s[74:75]
	s_nop 7
	s_add_i32 s77, s40, -64
	s_cmp_lt_u32 s77, s44
	s_cselect_b32 s76, s70, s71
	v_min_f32_e32 v152, s76, v236
	v_min_f32_e32 v153, s76, v237
	v_min_f32_e32 v154, s76, v238
	v_min_f32_e32 v155, s76, v239
	s_waitcnt lgkmcnt(0)
	v_mfma_f32_16x16x32_bf16 v[236:239], v[220:223], v[48:51], 0
	v_mfma_f32_16x16x32_bf16 v[236:239], v[224:227], v[52:55], v[236:239]
	v_mfma_f32_16x16x32_bf16 v[244:247], v[220:223], v[56:59], 0
	v_mfma_f32_16x16x32_bf16 v[244:247], v[224:227], v[60:63], v[244:247]
	s_waitcnt vmcnt(26)
	ds_write_b128 v165, v[32:35]
	ds_write_b128 v165, v[36:39] offset:1152
	ds_read_b128 v[228:231], v175 offset:2304
	ds_read_b128 v[232:235], v175 offset:2368
	v_pk_mul_f32 v[152:153], v[152:153], s[72:73]
	v_pk_mul_f32 v[154:155], v[154:155], s[72:73]
	v_exp_f32_e32 v152, v152
	v_exp_f32_e32 v153, v153
	v_exp_f32_e32 v154, v154
	v_exp_f32_e32 v155, v155
	v_cndmask_b32_e64 v152, 0, v152, s[54:55]
	v_cndmask_b32_e64 v153, 0, v153, s[56:57]
	v_cndmask_b32_e64 v154, 0, v154, s[58:59]
	v_cndmask_b32_e64 v155, 0, v155, s[60:61]
	v_pk_add_f32 v[138:139], v[138:139], v[152:153]
	v_pk_add_f32 v[138:139], v[138:139], v[154:155]
	v_cvt_pk_bf16_f32 v112, v152, v153
	v_cvt_pk_bf16_f32 v113, v154, v155
	s_add_i32 s77, s40, -48
	s_cmp_lt_u32 s77, s44
	s_cselect_b32 s76, s70, s71
	v_min_f32_e32 v152, s76, v240
	v_min_f32_e32 v153, s76, v241
	v_min_f32_e32 v154, s76, v242
	v_min_f32_e32 v155, s76, v243
	v_min_f32_e32 v156, s76, v248
	v_min_f32_e32 v157, s76, v249
	v_min_f32_e32 v158, s76, v250
	v_min_f32_e32 v159, s76, v251
	s_waitcnt lgkmcnt(0)
	v_mfma_f32_16x16x32_bf16 v[240:243], v[228:231], v[48:51], 0
	v_mfma_f32_16x16x32_bf16 v[240:243], v[232:235], v[52:55], v[240:243]
	v_mfma_f32_16x16x32_bf16 v[248:251], v[228:231], v[56:59], 0
	v_mfma_f32_16x16x32_bf16 v[248:251], v[232:235], v[60:63], v[248:251]
	s_waitcnt vmcnt(24)
	ds_write_b128 v165, v[40:43] offset:2304
	ds_write_b128 v165, v[44:47] offset:3456
	ds_read_b128 v[204:207], v175
	ds_read_b128 v[208:211], v175 offset:64
	v_pk_mul_f32 v[152:153], v[152:153], s[72:73]
	v_pk_mul_f32 v[154:155], v[154:155], s[72:73]
	v_exp_f32_e32 v152, v152
	v_exp_f32_e32 v153, v153
	v_exp_f32_e32 v154, v154
	v_exp_f32_e32 v155, v155
	v_pk_add_f32 v[138:139], v[138:139], v[152:153]
	v_pk_add_f32 v[138:139], v[138:139], v[154:155]
	v_cvt_pk_bf16_f32 v114, v152, v153
	v_cvt_pk_bf16_f32 v115, v154, v155
	v_pk_mul_f32 v[156:157], v[156:157], s[72:73]
	v_pk_mul_f32 v[158:159], v[158:159], s[72:73]
	v_exp_f32_e32 v156, v156
	v_exp_f32_e32 v157, v157
	v_exp_f32_e32 v158, v158
	v_exp_f32_e32 v159, v159
	v_cndmask_b32_e64 v156, 0, v156, s[54:55]
	v_cndmask_b32_e64 v157, 0, v157, s[56:57]
	v_cndmask_b32_e64 v158, 0, v158, s[58:59]
	v_cndmask_b32_e64 v159, 0, v159, s[60:61]
	v_pk_add_f32 v[140:141], v[140:141], v[156:157]
	v_pk_add_f32 v[140:141], v[140:141], v[158:159]
	v_cvt_pk_bf16_f32 v186, v156, v157
	v_cvt_pk_bf16_f32 v187, v158, v159
	s_add_i32 s77, s40, -32
	s_cmp_lt_u32 s77, s44
	s_cselect_b32 s76, s70, s71
	v_min_f32_e32 v152, s76, v236
	v_min_f32_e32 v153, s76, v237
	v_min_f32_e32 v154, s76, v238
	v_min_f32_e32 v155, s76, v239
	v_min_f32_e32 v156, s76, v244
	v_min_f32_e32 v157, s76, v245
	v_min_f32_e32 v158, s76, v246
	v_min_f32_e32 v159, s76, v247
	s_waitcnt lgkmcnt(0)
	v_mfma_f32_16x16x32_bf16 v[236:239], v[204:207], v[48:51], 0
	v_mfma_f32_16x16x32_bf16 v[236:239], v[208:211], v[52:55], v[236:239]
	v_mfma_f32_16x16x32_bf16 v[244:247], v[204:207], v[56:59], 0
	v_mfma_f32_16x16x32_bf16 v[244:247], v[208:211], v[60:63], v[244:247]
	s_lshl_b32 s2, s41, s39
	s_lshl_b32 s2, s2, 7
	s_add_u32 s74, s26, s2
	s_addc_u32 s75, s27, 0
	s_add_i32 s2, s40, 64
	v_add_u32_e32 v137, s2, v164
	v_ashrrev_i32_e32 v137, 2, v137
	v_med3_i32 v137, v137, 0, s38
	v_lshl_add_u32 v137, v137, 9, v178
	global_load_dwordx4 v[32:35], v137, s[74:75]
	s_add_i32 s2, s40, 72
	v_add_u32_e32 v137, s2, v164
	v_ashrrev_i32_e32 v137, 2, v137
	v_med3_i32 v137, v137, 0, s38
	v_lshl_add_u32 v137, v137, 9, v178
	global_load_dwordx4 v[36:39], v137, s[74:75]
	s_add_i32 s2, s40, 80
	v_add_u32_e32 v137, s2, v164
	v_ashrrev_i32_e32 v137, 2, v137
	v_med3_i32 v137, v137, 0, s38
	v_lshl_add_u32 v137, v137, 9, v178
	global_load_dwordx4 v[40:43], v137, s[74:75]
	s_add_i32 s2, s40, 88
	v_add_u32_e32 v137, s2, v164
	v_ashrrev_i32_e32 v137, 2, v137
	v_med3_i32 v137, v137, 0, s38
	v_lshl_add_u32 v137, v137, 9, v178
	global_load_dwordx4 v[44:47], v137, s[74:75]
	s_waitcnt vmcnt(14)
	ds_write_b128 v165, v[120:123]
	ds_write_b128 v165, v[124:127] offset:1152
	ds_read_b128 v[212:215], v175 offset:2304
	ds_read_b128 v[216:219], v175 offset:2368
	v_pk_mul_f32 v[152:153], v[152:153], s[72:73]
	v_pk_mul_f32 v[154:155], v[154:155], s[72:73]
	v_exp_f32_e32 v152, v152
	v_exp_f32_e32 v153, v153
	v_exp_f32_e32 v154, v154
	v_exp_f32_e32 v155, v155
	v_pk_add_f32 v[138:139], v[138:139], v[152:153]
	v_pk_add_f32 v[138:139], v[138:139], v[154:155]
	v_cvt_pk_bf16_f32 v116, v152, v153
	v_cvt_pk_bf16_f32 v117, v154, v155
	v_pk_mul_f32 v[156:157], v[156:157], s[72:73]
	v_pk_mul_f32 v[158:159], v[158:159], s[72:73]
	v_exp_f32_e32 v156, v156
	v_exp_f32_e32 v157, v157
	v_exp_f32_e32 v158, v158
	v_exp_f32_e32 v159, v159
	v_pk_add_f32 v[140:141], v[140:141], v[156:157]
	v_pk_add_f32 v[140:141], v[140:141], v[158:159]
	v_cvt_pk_bf16_f32 v188, v156, v157
	v_cvt_pk_bf16_f32 v189, v158, v159
	s_add_i32 s77, s40, -16
	s_cmp_lt_u32 s77, s44
	s_cselect_b32 s76, s70, s71
	v_min_f32_e32 v152, s76, v240
	v_min_f32_e32 v153, s76, v241
	v_min_f32_e32 v154, s76, v242
	v_min_f32_e32 v155, s76, v243
	v_min_f32_e32 v156, s76, v248
	v_min_f32_e32 v157, s76, v249
	v_min_f32_e32 v158, s76, v250
	v_min_f32_e32 v159, s76, v251
	s_waitcnt lgkmcnt(0)
	v_mfma_f32_16x16x32_bf16 v[240:243], v[212:215], v[48:51], 0
	v_mfma_f32_16x16x32_bf16 v[240:243], v[216:219], v[52:55], v[240:243]
	v_mfma_f32_16x16x32_bf16 v[248:251], v[212:215], v[56:59], 0
	v_mfma_f32_16x16x32_bf16 v[248:251], v[216:219], v[60:63], v[248:251]
	s_waitcnt vmcnt(12)
	ds_write_b128 v165, v[192:195] offset:2304
	ds_write_b128 v165, v[196:199] offset:3456
	ds_read_b128 v[220:223], v175
	ds_read_b128 v[224:227], v175 offset:64
	v_pk_mul_f32 v[152:153], v[152:153], s[72:73]
	v_pk_mul_f32 v[154:155], v[154:155], s[72:73]
	v_exp_f32_e32 v152, v152
	v_exp_f32_e32 v153, v153
	v_exp_f32_e32 v154, v154
	v_exp_f32_e32 v155, v155
	v_pk_add_f32 v[138:139], v[138:139], v[152:153]
	v_pk_add_f32 v[138:139], v[138:139], v[154:155]
	v_cvt_pk_bf16_f32 v118, v152, v153
	v_cvt_pk_bf16_f32 v119, v154, v155
	v_pk_mul_f32 v[156:157], v[156:157], s[72:73]
	v_pk_mul_f32 v[158:159], v[158:159], s[72:73]
	v_exp_f32_e32 v156, v156
	v_exp_f32_e32 v157, v157
	v_exp_f32_e32 v158, v158
	v_exp_f32_e32 v159, v159
	v_pk_add_f32 v[140:141], v[140:141], v[156:157]
	v_pk_add_f32 v[140:141], v[140:141], v[158:159]
	v_cvt_pk_bf16_f32 v190, v156, v157
	v_cvt_pk_bf16_f32 v191, v158, v159
	s_add_i32 s77, s40, 0
	s_cmp_lt_u32 s77, s44
	s_cselect_b32 s76, s70, s71
	v_min_f32_e32 v152, s76, v236
	v_min_f32_e32 v153, s76, v237
	v_min_f32_e32 v154, s76, v238
	v_min_f32_e32 v155, s76, v239
	v_min_f32_e32 v156, s76, v244
	v_min_f32_e32 v157, s76, v245
	v_min_f32_e32 v158, s76, v246
	v_min_f32_e32 v159, s76, v247
	s_waitcnt lgkmcnt(0)
	v_mfma_f32_16x16x32_bf16 v[236:239], v[220:223], v[48:51], 0
	v_mfma_f32_16x16x32_bf16 v[236:239], v[224:227], v[52:55], v[236:239]
	v_mfma_f32_16x16x32_bf16 v[244:247], v[220:223], v[56:59], 0
	v_mfma_f32_16x16x32_bf16 v[244:247], v[224:227], v[60:63], v[244:247]
	s_waitcnt vmcnt(10)
	ds_write_b128 v165, v[0:3]
	ds_write_b128 v165, v[4:7] offset:1152
	ds_read_b128 v[228:231], v175 offset:2304
	ds_read_b128 v[232:235], v175 offset:2368
	v_pk_mul_f32 v[152:153], v[152:153], s[72:73]
	v_pk_mul_f32 v[154:155], v[154:155], s[72:73]
	v_exp_f32_e32 v152, v152
	v_exp_f32_e32 v153, v153
	v_exp_f32_e32 v154, v154
	v_exp_f32_e32 v155, v155
	v_pk_add_f32 v[138:139], v[138:139], v[152:153]
	v_pk_add_f32 v[138:139], v[138:139], v[154:155]
	v_cvt_pk_bf16_f32 v120, v152, v153
	v_cvt_pk_bf16_f32 v121, v154, v155
	v_pk_mul_f32 v[156:157], v[156:157], s[72:73]
	v_pk_mul_f32 v[158:159], v[158:159], s[72:73]
	v_exp_f32_e32 v156, v156
	v_exp_f32_e32 v157, v157
	v_exp_f32_e32 v158, v158
	v_exp_f32_e32 v159, v159
	v_pk_add_f32 v[140:141], v[140:141], v[156:157]
	v_pk_add_f32 v[140:141], v[140:141], v[158:159]
	v_cvt_pk_bf16_f32 v192, v156, v157
	v_cvt_pk_bf16_f32 v193, v158, v159
	s_add_i32 s77, s40, 16
	s_cmp_lt_u32 s77, s44
	s_cselect_b32 s76, s70, s71
	v_min_f32_e32 v152, s76, v240
	v_min_f32_e32 v153, s76, v241
	v_min_f32_e32 v154, s76, v242
	v_min_f32_e32 v155, s76, v243
	v_min_f32_e32 v156, s76, v248
	v_min_f32_e32 v157, s76, v249
	v_min_f32_e32 v158, s76, v250
	v_min_f32_e32 v159, s76, v251
	s_waitcnt lgkmcnt(0)
	v_mfma_f32_16x16x32_bf16 v[240:243], v[228:231], v[48:51], 0
	v_mfma_f32_16x16x32_bf16 v[240:243], v[232:235], v[52:55], v[240:243]
	v_mfma_f32_16x16x32_bf16 v[248:251], v[228:231], v[56:59], 0
	v_mfma_f32_16x16x32_bf16 v[248:251], v[232:235], v[60:63], v[248:251]
	s_waitcnt vmcnt(8)
	ds_write_b128 v165, v[8:11] offset:2304
	ds_write_b128 v165, v[12:15] offset:3456
	ds_read_b128 v[204:207], v175
	ds_read_b128 v[208:211], v175 offset:64
	v_pk_mul_f32 v[152:153], v[152:153], s[72:73]
	v_pk_mul_f32 v[154:155], v[154:155], s[72:73]
	v_exp_f32_e32 v152, v152
	v_exp_f32_e32 v153, v153
	v_exp_f32_e32 v154, v154
	v_exp_f32_e32 v155, v155
	v_pk_add_f32 v[138:139], v[138:139], v[152:153]
	v_pk_add_f32 v[138:139], v[138:139], v[154:155]
	v_cvt_pk_bf16_f32 v122, v152, v153
	v_cvt_pk_bf16_f32 v123, v154, v155
	v_pk_mul_f32 v[156:157], v[156:157], s[72:73]
	v_pk_mul_f32 v[158:159], v[158:159], s[72:73]
	v_exp_f32_e32 v156, v156
	v_exp_f32_e32 v157, v157
	v_exp_f32_e32 v158, v158
	v_exp_f32_e32 v159, v159
	v_pk_add_f32 v[140:141], v[140:141], v[156:157]
	v_pk_add_f32 v[140:141], v[140:141], v[158:159]
	v_cvt_pk_bf16_f32 v194, v156, v157
	v_cvt_pk_bf16_f32 v195, v158, v159
	s_add_i32 s77, s40, 32
	s_cmp_lt_u32 s77, s44
	s_cselect_b32 s76, s70, s71
	v_min_f32_e32 v152, s76, v236
	v_min_f32_e32 v153, s76, v237
	v_min_f32_e32 v154, s76, v238
	v_min_f32_e32 v155, s76, v239
	v_min_f32_e32 v156, s76, v244
	v_min_f32_e32 v157, s76, v245
	v_min_f32_e32 v158, s76, v246
	v_min_f32_e32 v159, s76, v247
	s_waitcnt lgkmcnt(0)
	v_mfma_f32_16x16x32_bf16 v[236:239], v[204:207], v[48:51], 0
	v_mfma_f32_16x16x32_bf16 v[236:239], v[208:211], v[52:55], v[236:239]
	v_mfma_f32_16x16x32_bf16 v[244:247], v[204:207], v[56:59], 0
	v_mfma_f32_16x16x32_bf16 v[244:247], v[208:211], v[60:63], v[244:247]
	ds_read_b128 v[212:215], v175 offset:2304
	ds_read_b128 v[216:219], v175 offset:2368
	v_pk_mul_f32 v[152:153], v[152:153], s[72:73]
	v_pk_mul_f32 v[154:155], v[154:155], s[72:73]
	v_exp_f32_e32 v152, v152
	v_exp_f32_e32 v153, v153
	v_exp_f32_e32 v154, v154
	v_exp_f32_e32 v155, v155
	v_pk_add_f32 v[138:139], v[138:139], v[152:153]
	v_pk_add_f32 v[138:139], v[138:139], v[154:155]
	v_cvt_pk_bf16_f32 v124, v152, v153
	v_cvt_pk_bf16_f32 v125, v154, v155
	v_pk_mul_f32 v[156:157], v[156:157], s[72:73]
	v_pk_mul_f32 v[158:159], v[158:159], s[72:73]
	v_exp_f32_e32 v156, v156
	v_exp_f32_e32 v157, v157
	v_exp_f32_e32 v158, v158
	v_exp_f32_e32 v159, v159
	v_pk_add_f32 v[140:141], v[140:141], v[156:157]
	v_pk_add_f32 v[140:141], v[140:141], v[158:159]
	v_cvt_pk_bf16_f32 v196, v156, v157
	v_cvt_pk_bf16_f32 v197, v158, v159
	s_add_i32 s77, s40, 48
	s_cmp_lt_u32 s77, s44
	s_cselect_b32 s76, s70, s71
	v_min_f32_e32 v152, s76, v240
	v_min_f32_e32 v153, s76, v241
	v_min_f32_e32 v154, s76, v242
	v_min_f32_e32 v155, s76, v243
	v_min_f32_e32 v156, s76, v248
	v_min_f32_e32 v157, s76, v249
	v_min_f32_e32 v158, s76, v250
	v_min_f32_e32 v159, s76, v251
	s_waitcnt lgkmcnt(0)
	v_mfma_f32_16x16x32_bf16 v[248:251], v[212:215], v[56:59], 0
	v_mfma_f32_16x16x32_bf16 v[248:251], v[216:219], v[60:63], v[248:251]
	v_pk_mul_f32 v[152:153], v[152:153], s[72:73]
	v_pk_mul_f32 v[154:155], v[154:155], s[72:73]
	v_exp_f32_e32 v152, v152
	v_exp_f32_e32 v153, v153
	v_exp_f32_e32 v154, v154
	v_exp_f32_e32 v155, v155
	v_pk_add_f32 v[138:139], v[138:139], v[152:153]
	v_pk_add_f32 v[138:139], v[138:139], v[154:155]
	v_cvt_pk_bf16_f32 v126, v152, v153
	v_cvt_pk_bf16_f32 v127, v154, v155
	v_pk_mul_f32 v[156:157], v[156:157], s[72:73]
	v_pk_mul_f32 v[158:159], v[158:159], s[72:73]
	v_exp_f32_e32 v156, v156
	v_exp_f32_e32 v157, v157
	v_exp_f32_e32 v158, v158
	v_exp_f32_e32 v159, v159
	v_pk_add_f32 v[140:141], v[140:141], v[156:157]
	v_pk_add_f32 v[140:141], v[140:141], v[158:159]
	v_cvt_pk_bf16_f32 v198, v156, v157
	v_cvt_pk_bf16_f32 v199, v158, v159
	s_add_i32 s77, s40, 64
	s_cmp_lt_u32 s77, s44
	s_cselect_b32 s76, s70, s71
	v_min_f32_e32 v152, s76, v236
	v_min_f32_e32 v153, s76, v237
	v_min_f32_e32 v154, s76, v238
	v_min_f32_e32 v155, s76, v239
	v_min_f32_e32 v156, s76, v244
	v_min_f32_e32 v157, s76, v245
	v_min_f32_e32 v158, s76, v246
	v_min_f32_e32 v159, s76, v247
	v_pk_mul_f32 v[152:153], v[152:153], s[72:73]
	v_pk_mul_f32 v[154:155], v[154:155], s[72:73]
	v_exp_f32_e32 v152, v152
	v_exp_f32_e32 v153, v153
	v_exp_f32_e32 v154, v154
	v_exp_f32_e32 v155, v155
	v_cndmask_b32_e64 v152, 0, v152, s[62:63]
	v_cndmask_b32_e64 v153, 0, v153, s[64:65]
	v_cndmask_b32_e64 v154, 0, v154, s[66:67]
	v_cndmask_b32_e64 v155, 0, v155, s[68:69]
	v_pk_add_f32 v[138:139], v[138:139], v[152:153]
	v_pk_add_f32 v[138:139], v[138:139], v[154:155]
	v_cvt_pk_bf16_f32 v128, v152, v153
	v_cvt_pk_bf16_f32 v129, v154, v155
	v_pk_mul_f32 v[156:157], v[156:157], s[72:73]
	v_pk_mul_f32 v[158:159], v[158:159], s[72:73]
	v_exp_f32_e32 v156, v156
	v_exp_f32_e32 v157, v157
	v_exp_f32_e32 v158, v158
	v_exp_f32_e32 v159, v159
	v_pk_add_f32 v[140:141], v[140:141], v[156:157]
	v_pk_add_f32 v[140:141], v[140:141], v[158:159]
	v_cvt_pk_bf16_f32 v200, v156, v157
	v_cvt_pk_bf16_f32 v201, v158, v159
	s_add_i32 s77, s40, 80
	s_cmp_lt_u32 s77, s44
	s_cselect_b32 s76, s70, s71
	v_min_f32_e32 v156, s76, v248
	v_min_f32_e32 v157, s76, v249
	v_min_f32_e32 v158, s76, v250
	v_min_f32_e32 v159, s76, v251
	v_pk_mul_f32 v[156:157], v[156:157], s[72:73]
	v_pk_mul_f32 v[158:159], v[158:159], s[72:73]
	v_exp_f32_e32 v156, v156
	v_exp_f32_e32 v157, v157
	v_exp_f32_e32 v158, v158
	v_exp_f32_e32 v159, v159
	v_cndmask_b32_e64 v156, 0, v156, s[62:63]
	v_cndmask_b32_e64 v157, 0, v157, s[64:65]
	v_cndmask_b32_e64 v158, 0, v158, s[66:67]
	v_cndmask_b32_e64 v159, 0, v159, s[68:69]
	v_pk_add_f32 v[140:141], v[140:141], v[156:157]
	v_pk_add_f32 v[140:141], v[140:141], v[158:159]
	v_cvt_pk_bf16_f32 v202, v156, v157
	v_cvt_pk_bf16_f32 v203, v158, v159
	v_add_f32_e32 v132, v138, v139
	v_add_f32_e32 v133, v140, v141
	v_add_u32_e32 v134, s42, v160
	v_lshlrev_b32_e32 v134, 4, v134
	v_add_u32_e32 v134, s43, v134
	v_subrev_u32_e32 v135, s15, v134
	v_lshrrev_b32_e32 v136, 4, v135
	v_add_u32_e32 v136, v136, v135
	v_mad_u32_u24 v176, v136, s79, v161
	v_lshl_add_u32 v177, v135, 2, s80
	s_and_b32 s2, s43, 3
	s_lshl_b32 s2, s2, s13
	s_lshr_b32 s3, s43, 2
	s_add_i32 s2, s2, s3
	s_lshl_b32 s2, s2, 7
	s_add_u32 s86, s20, s2
	s_addc_u32 s87, s21, 0
	s_add_i32 s2, s42, -64
	v_add_u32_e32 v136, s2, v164
	v_med3_i32 v136, v136, 0, s14
	v_lshl_add_u32 v136, v136, 9, v162
	global_load_dwordx4 v[0:3], v136, s[86:87]
	s_add_i32 s2, s42, -56
	v_add_u32_e32 v135, s2, v164
	v_med3_i32 v135, v135, 0, s14
	v_lshl_add_u32 v135, v135, 9, v162
	global_load_dwordx4 v[4:7], v135, s[86:87]
	s_add_i32 s2, s42, -48
	v_add_u32_e32 v136, s2, v164
	v_med3_i32 v136, v136, 0, s14
	v_lshl_add_u32 v136, v136, 9, v162
	global_load_dwordx4 v[8:11], v136, s[86:87]
	s_add_i32 s2, s42, -40
	v_add_u32_e32 v135, s2, v164
	v_med3_i32 v135, v135, 0, s14
	v_lshl_add_u32 v135, v135, 9, v162
	global_load_dwordx4 v[12:15], v135, s[86:87]
	ds_bpermute_b32 v142, v167, v132
	ds_bpermute_b32 v143, v167, v133
	ds_write_b128 v165, v[64:67]
	ds_write_b128 v165, v[68:71] offset:1152
	ds_write_b128 v165, v[72:75] offset:2304
	ds_write_b128 v165, v[76:79] offset:3456
	s_waitcnt lgkmcnt(0)
	v_add_f32_e32 v132, v132, v142
	v_add_f32_e32 v133, v133, v143
	ds_bpermute_b32 v142, v168, v132
	ds_bpermute_b32 v143, v168, v133
	ds_read_b64_tr_b16 v[236:237], v166
	ds_read_b64_tr_b16 v[238:239], v166 offset:2304
	ds_read_b64_tr_b16 v[240:241], v166 offset:32
	ds_read_b64_tr_b16 v[242:243], v166 offset:2336
	ds_read_b64_tr_b16 v[244:245], v166 offset:64
	ds_read_b64_tr_b16 v[246:247], v166 offset:2368
	ds_read_b64_tr_b16 v[248:249], v166 offset:96
	ds_read_b64_tr_b16 v[250:251], v166 offset:2400
	s_waitcnt lgkmcnt(0)
	v_add_f32_e32 v132, v132, v142
	v_add_f32_e32 v133, v133, v143
	ds_write_b128 v165, v[80:83]
	ds_write_b128 v165, v[84:87] offset:1152
	ds_write_b128 v165, v[88:91] offset:2304
	ds_write_b128 v165, v[92:95] offset:3456
	v_mfma_f32_16x16x32_bf16 v[204:207], v[236:239], v[112:115], 0
	v_mfma_f32_16x16x32_bf16 v[208:211], v[240:243], v[112:115], 0
	v_mfma_f32_16x16x32_bf16 v[212:215], v[244:247], v[112:115], 0
	v_mfma_f32_16x16x32_bf16 v[216:219], v[248:251], v[112:115], 0
	v_mfma_f32_16x16x32_bf16 v[220:223], v[236:239], v[184:187], 0
	v_mfma_f32_16x16x32_bf16 v[224:227], v[240:243], v[184:187], 0
	v_mfma_f32_16x16x32_bf16 v[228:231], v[244:247], v[184:187], 0
	v_mfma_f32_16x16x32_bf16 v[232:235], v[248:251], v[184:187], 0
	s_waitcnt lgkmcnt(0)
	ds_read_b64_tr_b16 v[236:237], v166
	ds_read_b64_tr_b16 v[238:239], v166 offset:2304
	ds_read_b64_tr_b16 v[240:241], v166 offset:32
	ds_read_b64_tr_b16 v[242:243], v166 offset:2336
	ds_read_b64_tr_b16 v[244:245], v166 offset:64
	ds_read_b64_tr_b16 v[246:247], v166 offset:2368
	ds_read_b64_tr_b16 v[248:249], v166 offset:96
	ds_read_b64_tr_b16 v[250:251], v166 offset:2400
	s_waitcnt lgkmcnt(0)
	ds_write_b128 v165, v[96:99]
	ds_write_b128 v165, v[100:103] offset:1152
	ds_write_b128 v165, v[104:107] offset:2304
	ds_write_b128 v165, v[108:111] offset:3456
	v_mfma_f32_16x16x32_bf16 v[204:207], v[236:239], v[116:119], v[204:207]
	v_mfma_f32_16x16x32_bf16 v[208:211], v[240:243], v[116:119], v[208:211]
	v_mfma_f32_16x16x32_bf16 v[212:215], v[244:247], v[116:119], v[212:215]
	v_mfma_f32_16x16x32_bf16 v[216:219], v[248:251], v[116:119], v[216:219]
	v_mfma_f32_16x16x32_bf16 v[220:223], v[236:239], v[188:191], v[220:223]
	v_mfma_f32_16x16x32_bf16 v[224:227], v[240:243], v[188:191], v[224:227]
	v_mfma_f32_16x16x32_bf16 v[228:231], v[244:247], v[188:191], v[228:231]
	v_mfma_f32_16x16x32_bf16 v[232:235], v[248:251], v[188:191], v[232:235]
	s_waitcnt lgkmcnt(0)
	ds_read_b64_tr_b16 v[236:237], v166
	ds_read_b64_tr_b16 v[238:239], v166 offset:2304
	ds_read_b64_tr_b16 v[240:241], v166 offset:32
	ds_read_b64_tr_b16 v[242:243], v166 offset:2336
	ds_read_b64_tr_b16 v[244:245], v166 offset:64
	ds_read_b64_tr_b16 v[246:247], v166 offset:2368
	ds_read_b64_tr_b16 v[248:249], v166 offset:96
	ds_read_b64_tr_b16 v[250:251], v166 offset:2400
	s_waitcnt lgkmcnt(0)
	s_waitcnt vmcnt(8)
	ds_write_b128 v165, v[16:19]
	ds_write_b128 v165, v[20:23] offset:1152
	ds_write_b128 v165, v[24:27] offset:2304
	ds_write_b128 v165, v[28:31] offset:3456
	v_mfma_f32_16x16x32_bf16 v[204:207], v[236:239], v[120:123], v[204:207]
	v_mfma_f32_16x16x32_bf16 v[208:211], v[240:243], v[120:123], v[208:211]
	v_mfma_f32_16x16x32_bf16 v[212:215], v[244:247], v[120:123], v[212:215]
	v_mfma_f32_16x16x32_bf16 v[216:219], v[248:251], v[120:123], v[216:219]
	v_mfma_f32_16x16x32_bf16 v[220:223], v[236:239], v[192:195], v[220:223]
	v_mfma_f32_16x16x32_bf16 v[224:227], v[240:243], v[192:195], v[224:227]
	v_mfma_f32_16x16x32_bf16 v[228:231], v[244:247], v[192:195], v[228:231]
	v_mfma_f32_16x16x32_bf16 v[232:235], v[248:251], v[192:195], v[232:235]
	s_waitcnt lgkmcnt(0)
	ds_read_b64_tr_b16 v[236:237], v166
	ds_read_b64_tr_b16 v[238:239], v166 offset:2304
	ds_read_b64_tr_b16 v[240:241], v166 offset:32
	ds_read_b64_tr_b16 v[242:243], v166 offset:2336
	ds_read_b64_tr_b16 v[244:245], v166 offset:64
	ds_read_b64_tr_b16 v[246:247], v166 offset:2368
	ds_read_b64_tr_b16 v[248:249], v166 offset:96
	ds_read_b64_tr_b16 v[250:251], v166 offset:2400
	s_waitcnt lgkmcnt(0)
	s_add_i32 s2, s42, -32
	v_add_u32_e32 v136, s2, v164
	v_med3_i32 v136, v136, 0, s14
	v_lshl_add_u32 v136, v136, 9, v162
	global_load_dwordx4 v[16:19], v136, s[86:87]
	s_add_i32 s2, s42, -24
	v_add_u32_e32 v135, s2, v164
	v_med3_i32 v135, v135, 0, s14
	v_lshl_add_u32 v135, v135, 9, v162
	global_load_dwordx4 v[20:23], v135, s[86:87]
	s_add_i32 s2, s42, -16
	v_add_u32_e32 v136, s2, v164
	v_med3_i32 v136, v136, 0, s14
	v_lshl_add_u32 v136, v136, 9, v162
	global_load_dwordx4 v[24:27], v136, s[86:87]
	s_add_i32 s2, s42, -8
	v_add_u32_e32 v135, s2, v164
	v_med3_i32 v135, v135, 0, s14
	v_lshl_add_u32 v135, v135, 9, v162
	global_load_dwordx4 v[28:31], v135, s[86:87]
	s_waitcnt vmcnt(8)
	ds_write_b128 v165, v[32:35]
	ds_write_b128 v165, v[36:39] offset:1152
	ds_write_b128 v165, v[40:43] offset:2304
	ds_write_b128 v165, v[44:47] offset:3456
	v_mfma_f32_16x16x32_bf16 v[204:207], v[236:239], v[124:127], v[204:207]
	v_mfma_f32_16x16x32_bf16 v[208:211], v[240:243], v[124:127], v[208:211]
	v_mfma_f32_16x16x32_bf16 v[212:215], v[244:247], v[124:127], v[212:215]
	v_mfma_f32_16x16x32_bf16 v[216:219], v[248:251], v[124:127], v[216:219]
	v_mfma_f32_16x16x32_bf16 v[220:223], v[236:239], v[196:199], v[220:223]
	v_mfma_f32_16x16x32_bf16 v[224:227], v[240:243], v[196:199], v[224:227]
	v_mfma_f32_16x16x32_bf16 v[228:231], v[244:247], v[196:199], v[228:231]
	v_mfma_f32_16x16x32_bf16 v[232:235], v[248:251], v[196:199], v[232:235]
	s_waitcnt lgkmcnt(0)
	ds_read_b64_tr_b16 v[236:237], v166
	ds_read_b64_tr_b16 v[238:239], v166 offset:2304
	ds_read_b64_tr_b16 v[240:241], v166 offset:32
	ds_read_b64_tr_b16 v[242:243], v166 offset:2336
	ds_read_b64_tr_b16 v[244:245], v166 offset:64
	ds_read_b64_tr_b16 v[246:247], v166 offset:2368
	ds_read_b64_tr_b16 v[248:249], v166 offset:96
	ds_read_b64_tr_b16 v[250:251], v166 offset:2400
	s_waitcnt lgkmcnt(0)
	s_add_i32 s2, s42, 0
	v_add_u32_e32 v136, s2, v164
	v_med3_i32 v136, v136, 0, s14
	v_lshl_add_u32 v136, v136, 9, v162
	global_load_dwordx4 v[32:35], v136, s[86:87]
	s_add_i32 s2, s42, 8
	v_add_u32_e32 v135, s2, v164
	v_med3_i32 v135, v135, 0, s14
	v_lshl_add_u32 v135, v135, 9, v162
	global_load_dwordx4 v[36:39], v135, s[86:87]
	s_add_i32 s2, s42, 16
	v_add_u32_e32 v136, s2, v164
	v_med3_i32 v136, v136, 0, s14
	v_lshl_add_u32 v136, v136, 9, v162
	global_load_dwordx4 v[40:43], v136, s[86:87]
	s_add_i32 s2, s42, 24
	v_add_u32_e32 v135, s2, v164
	v_med3_i32 v135, v135, 0, s14
	v_lshl_add_u32 v135, v135, 9, v162
	global_load_dwordx4 v[44:47], v135, s[86:87]
	v_mfma_f32_16x16x32_bf16 v[204:207], v[236:239], v[128:131], v[204:207]
	v_mfma_f32_16x16x32_bf16 v[208:211], v[240:243], v[128:131], v[208:211]
	v_mfma_f32_16x16x32_bf16 v[212:215], v[244:247], v[128:131], v[212:215]
	v_mfma_f32_16x16x32_bf16 v[216:219], v[248:251], v[128:131], v[216:219]
	v_mfma_f32_16x16x32_bf16 v[220:223], v[236:239], v[200:203], v[220:223]
	v_mfma_f32_16x16x32_bf16 v[224:227], v[240:243], v[200:203], v[224:227]
	v_mfma_f32_16x16x32_bf16 v[228:231], v[244:247], v[200:203], v[228:231]
	v_mfma_f32_16x16x32_bf16 v[232:235], v[248:251], v[200:203], v[232:235]
	s_add_i32 s2, s42, 32
	v_add_u32_e32 v136, s2, v164
	v_med3_i32 v136, v136, 0, s14
	v_lshl_add_u32 v136, v136, 9, v162
	global_load_dwordx4 v[120:123], v136, s[86:87]
	s_add_i32 s2, s42, 40
	v_add_u32_e32 v135, s2, v164
	v_med3_i32 v135, v135, 0, s14
	v_lshl_add_u32 v135, v135, 9, v162
	global_load_dwordx4 v[124:127], v135, s[86:87]
	s_add_i32 s2, s42, 48
	v_add_u32_e32 v136, s2, v164
	v_med3_i32 v136, v136, 0, s14
	v_lshl_add_u32 v136, v136, 9, v162
	global_load_dwordx4 v[192:195], v136, s[86:87]
	s_add_i32 s2, s42, 56
	v_add_u32_e32 v135, s2, v164
	v_med3_i32 v135, v135, 0, s14
	v_lshl_add_u32 v135, v135, 9, v162
	global_load_dwordx4 v[196:199], v135, s[86:87]
	s_and_b32 s2, s43, 3
	s_lshl_b32 s2, s2, s13
	s_lshr_b32 s3, s43, 2
	s_add_i32 s2, s2, s3
	s_lshl_b32 s2, s2, 7
	s_add_u32 s74, s22, s2
	s_addc_u32 s75, s23, 0
	s_add_i32 s2, s42, -64
	v_add_u32_e32 v137, s2, v164
	v_med3_i32 v137, v137, 0, s14
	v_lshl_add_u32 v137, v137, 9, v162
	global_load_dwordx4 v[64:67], v137, s[74:75]
	s_add_i32 s2, s42, -56
	v_add_u32_e32 v137, s2, v164
	v_med3_i32 v137, v137, 0, s14
	v_lshl_add_u32 v137, v137, 9, v162
	global_load_dwordx4 v[68:71], v137, s[74:75]
	s_add_i32 s2, s42, -48
	v_add_u32_e32 v137, s2, v164
	v_med3_i32 v137, v137, 0, s14
	v_lshl_add_u32 v137, v137, 9, v162
	global_load_dwordx4 v[72:75], v137, s[74:75]
	s_add_i32 s2, s42, -40
	v_add_u32_e32 v137, s2, v164
	v_med3_i32 v137, v137, 0, s14
	v_lshl_add_u32 v137, v137, 9, v162
	global_load_dwordx4 v[76:79], v137, s[74:75]
	s_and_b32 s2, s43, 3
	s_lshl_b32 s2, s2, s13
	s_lshr_b32 s3, s43, 2
	s_add_i32 s2, s2, s3
	s_lshl_b32 s2, s2, 7
	s_add_u32 s74, s22, s2
	s_addc_u32 s75, s23, 0
	s_add_i32 s2, s42, -32
	v_add_u32_e32 v137, s2, v164
	v_med3_i32 v137, v137, 0, s14
	v_lshl_add_u32 v137, v137, 9, v162
	global_load_dwordx4 v[80:83], v137, s[74:75]
	s_add_i32 s2, s42, -24
	v_add_u32_e32 v137, s2, v164
	v_med3_i32 v137, v137, 0, s14
	v_lshl_add_u32 v137, v137, 9, v162
	global_load_dwordx4 v[84:87], v137, s[74:75]
	s_add_i32 s2, s42, -16
	v_add_u32_e32 v137, s2, v164
	v_med3_i32 v137, v137, 0, s14
	v_lshl_add_u32 v137, v137, 9, v162
	global_load_dwordx4 v[88:91], v137, s[74:75]
	s_add_i32 s2, s42, -8
	v_add_u32_e32 v137, s2, v164
	v_med3_i32 v137, v137, 0, s14
	v_lshl_add_u32 v137, v137, 9, v162
	global_load_dwordx4 v[92:95], v137, s[74:75]
	s_and_b32 s2, s43, 3
	s_lshl_b32 s2, s2, s13
	s_lshr_b32 s3, s43, 2
	s_add_i32 s2, s2, s3
	s_lshl_b32 s2, s2, 7
	s_add_u32 s74, s22, s2
	s_addc_u32 s75, s23, 0
	s_add_i32 s2, s42, 0
	v_add_u32_e32 v137, s2, v164
	v_med3_i32 v137, v137, 0, s14
	v_lshl_add_u32 v137, v137, 9, v162
	global_load_dwordx4 v[96:99], v137, s[74:75]
	s_add_i32 s2, s42, 8
	v_add_u32_e32 v137, s2, v164
	v_med3_i32 v137, v137, 0, s14
	v_lshl_add_u32 v137, v137, 9, v162
	global_load_dwordx4 v[100:103], v137, s[74:75]
	s_add_i32 s2, s42, 16
	v_add_u32_e32 v137, s2, v164
	v_med3_i32 v137, v137, 0, s14
	v_lshl_add_u32 v137, v137, 9, v162
	global_load_dwordx4 v[104:107], v137, s[74:75]
	s_add_i32 s2, s42, 24
	v_add_u32_e32 v137, s2, v164
	v_med3_i32 v137, v137, 0, s14
	v_lshl_add_u32 v137, v137, 9, v162
	global_load_dwordx4 v[108:111], v137, s[74:75]
	s_waitcnt lgkmcnt(0)
	s_barrier
	ds_read_b128 v[236:239], v173 offset:0
	ds_read_b128 v[240:243], v173 offset:64
	ds_read_b128 v[244:247], v173 offset:128
	ds_read_b128 v[248:251], v173 offset:192
	ds_read_b32 v142, v174 offset:0
	s_waitcnt lgkmcnt(0)
	v_add_f32_e32 v204, v236, v204
	v_add_f32_e32 v205, v237, v205
	v_add_f32_e32 v206, v238, v206
	v_add_f32_e32 v207, v239, v207
	v_add_f32_e32 v208, v240, v208
	v_add_f32_e32 v209, v241, v209
	v_add_f32_e32 v210, v242, v210
	v_add_f32_e32 v211, v243, v211
	v_add_f32_e32 v212, v244, v212
	v_add_f32_e32 v213, v245, v213
	v_add_f32_e32 v214, v246, v214
	v_add_f32_e32 v215, v247, v215
	v_add_f32_e32 v216, v248, v216
	v_add_f32_e32 v217, v249, v217
	v_add_f32_e32 v218, v250, v218
	v_add_f32_e32 v219, v251, v219
	v_add_f32_e32 v132, v142, v132
	ds_write_b128 v173, v[204:207] offset:0
	ds_write_b128 v173, v[208:211] offset:64
	ds_write_b128 v173, v[212:215] offset:128
	ds_write_b128 v173, v[216:219] offset:192
	ds_write_b32 v174, v132 offset:0
	ds_read_b128 v[236:239], v173 offset:18496
	ds_read_b128 v[240:243], v173 offset:18560
	ds_read_b128 v[244:247], v173 offset:18624
	ds_read_b128 v[248:251], v173 offset:18688
	ds_read_b32 v142, v174 offset:256
	s_waitcnt lgkmcnt(0)
	v_add_f32_e32 v220, v236, v220
	v_add_f32_e32 v221, v237, v221
	v_add_f32_e32 v222, v238, v222
	v_add_f32_e32 v223, v239, v223
	v_add_f32_e32 v224, v240, v224
	v_add_f32_e32 v225, v241, v225
	v_add_f32_e32 v226, v242, v226
	v_add_f32_e32 v227, v243, v227
	v_add_f32_e32 v228, v244, v228
	v_add_f32_e32 v229, v245, v229
	v_add_f32_e32 v230, v246, v230
	v_add_f32_e32 v231, v247, v231
	v_add_f32_e32 v232, v248, v232
	v_add_f32_e32 v233, v249, v233
	v_add_f32_e32 v234, v250, v234
	v_add_f32_e32 v235, v251, v235
	v_add_f32_e32 v133, v142, v133
	ds_write_b128 v173, v[220:223] offset:18496
	ds_write_b128 v173, v[224:227] offset:18560
	ds_write_b128 v173, v[228:231] offset:18624
	ds_write_b128 v173, v[232:235] offset:18688
	ds_write_b32 v174, v133 offset:256
	s_mov_b32 s40, s42
	s_mov_b32 s41, s43
	v_mov_b32_e32 v173, v176
	v_mov_b32_e32 v174, v177
	s_lshr_b32 s44, s33, 4
	s_lshr_b32 s42, s15, 4
	s_add_i32 s43, s0, 8
	v_subrev_u32_e32 v143, s80, v174
	v_lshl_add_u32 v143, v143, 5, v161
	v_add_u32_e32 v143, 0x1b500, v143
	ds_read_b128 v[48:51], v143
	ds_read_b128 v[52:55], v143 offset:64
	s_waitcnt lgkmcnt(0)
	v_mov_b32_e32 v138, 0
	v_mov_b32_e32 v139, 0
	s_waitcnt vmcnt(24)
	ds_write_b128 v165, v[0:3]
	ds_write_b128 v165, v[4:7] offset:1152
	ds_write_b128 v165, v[8:11] offset:2304
	ds_write_b128 v165, v[12:15] offset:3456
	s_waitcnt lgkmcnt(0)
	ds_read_b128 v[204:207], v175
	ds_read_b128 v[208:211], v175 offset:64
	ds_read_b128 v[212:215], v175 offset:2304
	ds_read_b128 v[216:219], v175 offset:2368
	s_and_b32 s2, s41, 3
	s_lshl_b32 s2, s2, s39
	s_lshr_b32 s3, s41, 2
	s_add_i32 s2, s2, s3
	s_lshl_b32 s2, s2, 7
	s_add_u32 s86, s24, s2
	s_addc_u32 s87, s25, 0
	s_add_i32 s2, s40, 64
	v_add_u32_e32 v136, s2, v164
	v_med3_i32 v136, v136, 0, s38
	v_lshl_add_u32 v136, v136, 9, v162
	global_load_dwordx4 v[0:3], v136, s[86:87]
	s_add_i32 s2, s40, 72
	v_add_u32_e32 v135, s2, v164
	v_med3_i32 v135, v135, 0, s38
	v_lshl_add_u32 v135, v135, 9, v162
	global_load_dwordx4 v[4:7], v135, s[86:87]
	s_waitcnt vmcnt(22)
	s_waitcnt lgkmcnt(0)
	ds_write_b128 v165, v[16:19]
	ds_write_b128 v165, v[20:23] offset:1152
	ds_write_b128 v165, v[24:27] offset:2304
	ds_write_b128 v165, v[28:31] offset:3456
	v_mfma_f32_16x16x32_bf16 v[236:239], v[204:207], v[48:51], 0
	v_mfma_f32_16x16x32_bf16 v[236:239], v[208:211], v[52:55], v[236:239]
	v_mfma_f32_16x16x32_bf16 v[240:243], v[212:215], v[48:51], 0
	v_mfma_f32_16x16x32_bf16 v[240:243], v[216:219], v[52:55], v[240:243]
	s_waitcnt lgkmcnt(0)
	ds_read_b128 v[220:223], v175
	ds_read_b128 v[224:227], v175 offset:64
	s_and_b32 s2, s41, 3
	s_lshl_b32 s2, s2, s39
	s_lshr_b32 s3, s41, 2
	s_add_i32 s2, s2, s3
	s_lshl_b32 s2, s2, 7
	s_add_u32 s74, s26, s2
	s_addc_u32 s75, s27, 0
	s_add_i32 s2, s40, 32
	v_add_u32_e32 v137, s2, v164
	v_med3_i32 v137, v137, 0, s38
	v_lshl_add_u32 v137, v137, 9, v162
	global_load_dwordx4 v[16:19], v137, s[74:75]
	s_add_i32 s2, s40, 40
	v_add_u32_e32 v137, s2, v164
	v_med3_i32 v137, v137, 0, s38
	v_lshl_add_u32 v137, v137, 9, v162
	global_load_dwordx4 v[20:23], v137, s[74:75]
	s_add_i32 s2, s40, 48
	v_add_u32_e32 v137, s2, v164
	v_med3_i32 v137, v137, 0, s38
	v_lshl_add_u32 v137, v137, 9, v162
	global_load_dwordx4 v[24:27], v137, s[74:75]
	s_add_i32 s2, s40, 56
	v_add_u32_e32 v137, s2, v164
	v_med3_i32 v137, v137, 0, s38
	v_lshl_add_u32 v137, v137, 9, v162
	global_load_dwordx4 v[28:31], v137, s[74:75]
	s_nop 7
	s_add_i32 s77, s40, -64
	s_cmp_lt_u32 s77, s44
	s_cselect_b32 s76, s70, s71
	v_min_f32_e32 v152, s76, v236
	v_min_f32_e32 v153, s76, v237
	v_min_f32_e32 v154, s76, v238
	v_min_f32_e32 v155, s76, v239
	s_waitcnt lgkmcnt(0)
	v_mfma_f32_16x16x32_bf16 v[236:239], v[220:223], v[48:51], 0
	v_mfma_f32_16x16x32_bf16 v[236:239], v[224:227], v[52:55], v[236:239]
	s_waitcnt vmcnt(24)
	ds_write_b128 v165, v[32:35]
	ds_write_b128 v165, v[36:39] offset:1152
	ds_read_b128 v[228:231], v175 offset:2304
	ds_read_b128 v[232:235], v175 offset:2368
	v_pk_mul_f32 v[152:153], v[152:153], s[72:73]
	v_pk_mul_f32 v[154:155], v[154:155], s[72:73]
	v_exp_f32_e32 v152, v152
	v_exp_f32_e32 v153, v153
	v_exp_f32_e32 v154, v154
	v_exp_f32_e32 v155, v155
	v_cndmask_b32_e64 v152, 0, v152, s[54:55]
	v_cndmask_b32_e64 v153, 0, v153, s[56:57]
	v_cndmask_b32_e64 v154, 0, v154, s[58:59]
	v_cndmask_b32_e64 v155, 0, v155, s[60:61]
	v_pk_add_f32 v[138:139], v[138:139], v[152:153]
	v_pk_add_f32 v[138:139], v[138:139], v[154:155]
	v_cvt_pk_bf16_f32 v112, v152, v153
	v_cvt_pk_bf16_f32 v113, v154, v155
	s_add_i32 s77, s40, -48
	s_cmp_lt_u32 s77, s44
	s_cselect_b32 s76, s70, s71
	v_min_f32_e32 v152, s76, v240
	v_min_f32_e32 v153, s76, v241
	v_min_f32_e32 v154, s76, v242
	v_min_f32_e32 v155, s76, v243
	s_waitcnt lgkmcnt(0)
	v_mfma_f32_16x16x32_bf16 v[240:243], v[228:231], v[48:51], 0
	v_mfma_f32_16x16x32_bf16 v[240:243], v[232:235], v[52:55], v[240:243]
	s_waitcnt vmcnt(22)
	ds_write_b128 v165, v[40:43] offset:2304
	ds_write_b128 v165, v[44:47] offset:3456
	ds_read_b128 v[204:207], v175
	ds_read_b128 v[208:211], v175 offset:64
	v_pk_mul_f32 v[152:153], v[152:153], s[72:73]
	v_pk_mul_f32 v[154:155], v[154:155], s[72:73]
	v_exp_f32_e32 v152, v152
	v_exp_f32_e32 v153, v153
	v_exp_f32_e32 v154, v154
	v_exp_f32_e32 v155, v155
	v_pk_add_f32 v[138:139], v[138:139], v[152:153]
	v_pk_add_f32 v[138:139], v[138:139], v[154:155]
	v_cvt_pk_bf16_f32 v114, v152, v153
	v_cvt_pk_bf16_f32 v115, v154, v155
	s_add_i32 s77, s40, -32
	s_cmp_lt_u32 s77, s44
	s_cselect_b32 s76, s70, s71
	v_min_f32_e32 v152, s76, v236
	v_min_f32_e32 v153, s76, v237
	v_min_f32_e32 v154, s76, v238
	v_min_f32_e32 v155, s76, v239
	s_waitcnt lgkmcnt(0)
	v_mfma_f32_16x16x32_bf16 v[236:239], v[204:207], v[48:51], 0
	v_mfma_f32_16x16x32_bf16 v[236:239], v[208:211], v[52:55], v[236:239]
	s_and_b32 s2, s41, 3
	s_lshl_b32 s2, s2, s39
	s_lshr_b32 s3, s41, 2
	s_add_i32 s2, s2, s3
	s_lshl_b32 s2, s2, 7
	s_add_u32 s74, s26, s2
	s_addc_u32 s75, s27, 0
	s_add_i32 s2, s40, 64
	v_add_u32_e32 v137, s2, v164
	v_med3_i32 v137, v137, 0, s38
	v_lshl_add_u32 v137, v137, 9, v162
	global_load_dwordx4 v[32:35], v137, s[74:75]
	s_add_i32 s2, s40, 72
	v_add_u32_e32 v137, s2, v164
	v_med3_i32 v137, v137, 0, s38
	v_lshl_add_u32 v137, v137, 9, v162
	global_load_dwordx4 v[36:39], v137, s[74:75]
	s_waitcnt vmcnt(22)
	ds_write_b128 v165, v[120:123]
	ds_write_b128 v165, v[124:127] offset:1152
	ds_read_b128 v[212:215], v175 offset:2304
	ds_read_b128 v[216:219], v175 offset:2368
	v_pk_mul_f32 v[152:153], v[152:153], s[72:73]
	v_pk_mul_f32 v[154:155], v[154:155], s[72:73]
	v_exp_f32_e32 v152, v152
	v_exp_f32_e32 v153, v153
	v_exp_f32_e32 v154, v154
	v_exp_f32_e32 v155, v155
	v_pk_add_f32 v[138:139], v[138:139], v[152:153]
	v_pk_add_f32 v[138:139], v[138:139], v[154:155]
	v_cvt_pk_bf16_f32 v116, v152, v153
	v_cvt_pk_bf16_f32 v117, v154, v155
	s_add_i32 s77, s40, -16
	s_cmp_lt_u32 s77, s44
	s_cselect_b32 s76, s70, s71
	v_min_f32_e32 v152, s76, v240
	v_min_f32_e32 v153, s76, v241
	v_min_f32_e32 v154, s76, v242
	v_min_f32_e32 v155, s76, v243
	s_waitcnt lgkmcnt(0)
	v_mfma_f32_16x16x32_bf16 v[240:243], v[212:215], v[48:51], 0
	v_mfma_f32_16x16x32_bf16 v[240:243], v[216:219], v[52:55], v[240:243]
	s_waitcnt vmcnt(20)
	ds_write_b128 v165, v[192:195] offset:2304
	ds_write_b128 v165, v[196:199] offset:3456
	ds_read_b128 v[220:223], v175
	ds_read_b128 v[224:227], v175 offset:64
	v_pk_mul_f32 v[152:153], v[152:153], s[72:73]
	v_pk_mul_f32 v[154:155], v[154:155], s[72:73]
	v_exp_f32_e32 v152, v152
	v_exp_f32_e32 v153, v153
	v_exp_f32_e32 v154, v154
	v_exp_f32_e32 v155, v155
	v_pk_add_f32 v[138:139], v[138:139], v[152:153]
	v_pk_add_f32 v[138:139], v[138:139], v[154:155]
	v_cvt_pk_bf16_f32 v118, v152, v153
	v_cvt_pk_bf16_f32 v119, v154, v155
	s_add_i32 s77, s40, 0
	s_cmp_lt_u32 s77, s44
	s_cselect_b32 s76, s70, s71
	v_min_f32_e32 v152, s76, v236
	v_min_f32_e32 v153, s76, v237
	v_min_f32_e32 v154, s76, v238
	v_min_f32_e32 v155, s76, v239
	s_waitcnt lgkmcnt(0)
	v_mfma_f32_16x16x32_bf16 v[236:239], v[220:223], v[48:51], 0
	v_mfma_f32_16x16x32_bf16 v[236:239], v[224:227], v[52:55], v[236:239]
	s_waitcnt vmcnt(6)
	ds_write_b128 v165, v[0:3]
	ds_write_b128 v165, v[4:7] offset:1152
	ds_read_b128 v[228:231], v175 offset:2304
	ds_read_b128 v[232:235], v175 offset:2368
	v_pk_mul_f32 v[152:153], v[152:153], s[72:73]
	v_pk_mul_f32 v[154:155], v[154:155], s[72:73]
	v_exp_f32_e32 v152, v152
	v_exp_f32_e32 v153, v153
	v_exp_f32_e32 v154, v154
	v_exp_f32_e32 v155, v155
	v_pk_add_f32 v[138:139], v[138:139], v[152:153]
	v_pk_add_f32 v[138:139], v[138:139], v[154:155]
	v_cvt_pk_bf16_f32 v120, v152, v153
	v_cvt_pk_bf16_f32 v121, v154, v155
	s_add_i32 s77, s40, 16
	s_cmp_lt_u32 s77, s44
	s_cselect_b32 s76, s70, s71
	v_min_f32_e32 v152, s76, v240
	v_min_f32_e32 v153, s76, v241
	v_min_f32_e32 v154, s76, v242
	v_min_f32_e32 v155, s76, v243
	s_waitcnt lgkmcnt(0)
	v_mfma_f32_16x16x32_bf16 v[240:243], v[228:231], v[48:51], 0
	v_mfma_f32_16x16x32_bf16 v[240:243], v[232:235], v[52:55], v[240:243]
	ds_read_b128 v[204:207], v175
	ds_read_b128 v[208:211], v175 offset:64
	v_pk_mul_f32 v[152:153], v[152:153], s[72:73]
	v_pk_mul_f32 v[154:155], v[154:155], s[72:73]
	v_exp_f32_e32 v152, v152
	v_exp_f32_e32 v153, v153
	v_exp_f32_e32 v154, v154
	v_exp_f32_e32 v155, v155
	v_pk_add_f32 v[138:139], v[138:139], v[152:153]
	v_pk_add_f32 v[138:139], v[138:139], v[154:155]
	v_cvt_pk_bf16_f32 v122, v152, v153
	v_cvt_pk_bf16_f32 v123, v154, v155
	s_add_i32 s77, s40, 32
	s_cmp_lt_u32 s77, s44
	s_cselect_b32 s76, s70, s71
	v_min_f32_e32 v152, s76, v236
	v_min_f32_e32 v153, s76, v237
	v_min_f32_e32 v154, s76, v238
	v_min_f32_e32 v155, s76, v239
	s_waitcnt lgkmcnt(0)
	v_mfma_f32_16x16x32_bf16 v[236:239], v[204:207], v[48:51], 0
	v_mfma_f32_16x16x32_bf16 v[236:239], v[208:211], v[52:55], v[236:239]
	v_pk_mul_f32 v[152:153], v[152:153], s[72:73]
	v_pk_mul_f32 v[154:155], v[154:155], s[72:73]
	v_exp_f32_e32 v152, v152
	v_exp_f32_e32 v153, v153
	v_exp_f32_e32 v154, v154
	v_exp_f32_e32 v155, v155
	v_pk_add_f32 v[138:139], v[138:139], v[152:153]
	v_pk_add_f32 v[138:139], v[138:139], v[154:155]
	v_cvt_pk_bf16_f32 v124, v152, v153
	v_cvt_pk_bf16_f32 v125, v154, v155
	s_add_i32 s77, s40, 48
	s_cmp_lt_u32 s77, s44
	s_cselect_b32 s76, s70, s71
	v_min_f32_e32 v152, s76, v240
	v_min_f32_e32 v153, s76, v241
	v_min_f32_e32 v154, s76, v242
	v_min_f32_e32 v155, s76, v243
	v_pk_mul_f32 v[152:153], v[152:153], s[72:73]
	v_pk_mul_f32 v[154:155], v[154:155], s[72:73]
	v_exp_f32_e32 v152, v152
	v_exp_f32_e32 v153, v153
	v_exp_f32_e32 v154, v154
	v_exp_f32_e32 v155, v155
	v_pk_add_f32 v[138:139], v[138:139], v[152:153]
	v_pk_add_f32 v[138:139], v[138:139], v[154:155]
	v_cvt_pk_bf16_f32 v126, v152, v153
	v_cvt_pk_bf16_f32 v127, v154, v155
	s_add_i32 s77, s40, 64
	s_cmp_lt_u32 s77, s44
	s_cselect_b32 s76, s70, s71
	v_min_f32_e32 v152, s76, v236
	v_min_f32_e32 v153, s76, v237
	v_min_f32_e32 v154, s76, v238
	v_min_f32_e32 v155, s76, v239
	v_pk_mul_f32 v[152:153], v[152:153], s[72:73]
	v_pk_mul_f32 v[154:155], v[154:155], s[72:73]
	v_exp_f32_e32 v152, v152
	v_exp_f32_e32 v153, v153
	v_exp_f32_e32 v154, v154
	v_exp_f32_e32 v155, v155
	v_cndmask_b32_e64 v152, 0, v152, s[62:63]
	v_cndmask_b32_e64 v153, 0, v153, s[64:65]
	v_cndmask_b32_e64 v154, 0, v154, s[66:67]
	v_cndmask_b32_e64 v155, 0, v155, s[68:69]
	v_pk_add_f32 v[138:139], v[138:139], v[152:153]
	v_pk_add_f32 v[138:139], v[138:139], v[154:155]
	v_cvt_pk_bf16_f32 v128, v152, v153
	v_cvt_pk_bf16_f32 v129, v154, v155
	v_add_f32_e32 v132, v138, v139
	v_add_u32_e32 v134, s42, v160
	v_lshlrev_b32_e32 v134, 4, v134
	v_add_u32_e32 v134, s43, v134
	v_subrev_u32_e32 v135, s15, v134
	v_lshrrev_b32_e32 v136, 4, v135
	v_add_u32_e32 v136, v136, v135
	v_mad_u32_u24 v176, v136, s79, v161
	v_lshl_add_u32 v177, v135, 2, s80
	s_and_b32 s2, s43, 3
	s_lshl_b32 s2, s2, s13
	s_lshr_b32 s3, s43, 2
	s_add_i32 s2, s2, s3
	s_lshl_b32 s2, s2, 7
	s_add_u32 s86, s20, s2
	s_addc_u32 s87, s21, 0
	s_add_i32 s2, s42, -64
	v_add_u32_e32 v136, s2, v164
	v_med3_i32 v136, v136, 0, s14
	v_lshl_add_u32 v136, v136, 9, v162
	global_load_dwordx4 v[0:3], v136, s[86:87]
	s_add_i32 s2, s42, -56
	v_add_u32_e32 v135, s2, v164
	v_med3_i32 v135, v135, 0, s14
	v_lshl_add_u32 v135, v135, 9, v162
	global_load_dwordx4 v[4:7], v135, s[86:87]
	s_add_i32 s2, s42, -48
	v_add_u32_e32 v136, s2, v164
	v_med3_i32 v136, v136, 0, s14
	v_lshl_add_u32 v136, v136, 9, v162
	global_load_dwordx4 v[8:11], v136, s[86:87]
	s_add_i32 s2, s42, -40
	v_add_u32_e32 v135, s2, v164
	v_med3_i32 v135, v135, 0, s14
	v_lshl_add_u32 v135, v135, 9, v162
	global_load_dwordx4 v[12:15], v135, s[86:87]
	ds_bpermute_b32 v142, v167, v132
	ds_write_b128 v165, v[64:67]
	ds_write_b128 v165, v[68:71] offset:1152
	ds_write_b128 v165, v[72:75] offset:2304
	ds_write_b128 v165, v[76:79] offset:3456
	s_waitcnt lgkmcnt(0)
	v_add_f32_e32 v132, v132, v142
	ds_bpermute_b32 v142, v168, v132
	ds_read_b64_tr_b16 v[236:237], v166
	ds_read_b64_tr_b16 v[238:239], v166 offset:2304
	ds_read_b64_tr_b16 v[240:241], v166 offset:32
	ds_read_b64_tr_b16 v[242:243], v166 offset:2336
	ds_read_b64_tr_b16 v[244:245], v166 offset:64
	ds_read_b64_tr_b16 v[246:247], v166 offset:2368
	ds_read_b64_tr_b16 v[248:249], v166 offset:96
	ds_read_b64_tr_b16 v[250:251], v166 offset:2400
	s_waitcnt lgkmcnt(0)
	v_add_f32_e32 v132, v132, v142
	ds_write_b128 v165, v[80:83]
	ds_write_b128 v165, v[84:87] offset:1152
	ds_write_b128 v165, v[88:91] offset:2304
	ds_write_b128 v165, v[92:95] offset:3456
	v_mfma_f32_16x16x32_bf16 v[204:207], v[236:239], v[112:115], 0
	v_mfma_f32_16x16x32_bf16 v[208:211], v[240:243], v[112:115], 0
	v_mfma_f32_16x16x32_bf16 v[212:215], v[244:247], v[112:115], 0
	v_mfma_f32_16x16x32_bf16 v[216:219], v[248:251], v[112:115], 0
	s_waitcnt lgkmcnt(0)
	ds_read_b64_tr_b16 v[236:237], v166
	ds_read_b64_tr_b16 v[238:239], v166 offset:2304
	ds_read_b64_tr_b16 v[240:241], v166 offset:32
	ds_read_b64_tr_b16 v[242:243], v166 offset:2336
	ds_read_b64_tr_b16 v[244:245], v166 offset:64
	ds_read_b64_tr_b16 v[246:247], v166 offset:2368
	ds_read_b64_tr_b16 v[248:249], v166 offset:96
	ds_read_b64_tr_b16 v[250:251], v166 offset:2400
	s_waitcnt lgkmcnt(0)
	ds_write_b128 v165, v[96:99]
	ds_write_b128 v165, v[100:103] offset:1152
	ds_write_b128 v165, v[104:107] offset:2304
	ds_write_b128 v165, v[108:111] offset:3456
	v_mfma_f32_16x16x32_bf16 v[204:207], v[236:239], v[116:119], v[204:207]
	v_mfma_f32_16x16x32_bf16 v[208:211], v[240:243], v[116:119], v[208:211]
	v_mfma_f32_16x16x32_bf16 v[212:215], v[244:247], v[116:119], v[212:215]
	v_mfma_f32_16x16x32_bf16 v[216:219], v[248:251], v[116:119], v[216:219]
	s_waitcnt lgkmcnt(0)
	ds_read_b64_tr_b16 v[236:237], v166
	ds_read_b64_tr_b16 v[238:239], v166 offset:2304
	ds_read_b64_tr_b16 v[240:241], v166 offset:32
	ds_read_b64_tr_b16 v[242:243], v166 offset:2336
	ds_read_b64_tr_b16 v[244:245], v166 offset:64
	ds_read_b64_tr_b16 v[246:247], v166 offset:2368
	ds_read_b64_tr_b16 v[248:249], v166 offset:96
	ds_read_b64_tr_b16 v[250:251], v166 offset:2400
	s_waitcnt lgkmcnt(0)
	s_waitcnt vmcnt(6)
	ds_write_b128 v165, v[16:19]
	ds_write_b128 v165, v[20:23] offset:1152
	ds_write_b128 v165, v[24:27] offset:2304
	ds_write_b128 v165, v[28:31] offset:3456
	v_mfma_f32_16x16x32_bf16 v[204:207], v[236:239], v[120:123], v[204:207]
	v_mfma_f32_16x16x32_bf16 v[208:211], v[240:243], v[120:123], v[208:211]
	v_mfma_f32_16x16x32_bf16 v[212:215], v[244:247], v[120:123], v[212:215]
	v_mfma_f32_16x16x32_bf16 v[216:219], v[248:251], v[120:123], v[216:219]
	s_waitcnt lgkmcnt(0)
	ds_read_b64_tr_b16 v[236:237], v166
	ds_read_b64_tr_b16 v[238:239], v166 offset:2304
	ds_read_b64_tr_b16 v[240:241], v166 offset:32
	ds_read_b64_tr_b16 v[242:243], v166 offset:2336
	ds_read_b64_tr_b16 v[244:245], v166 offset:64
	ds_read_b64_tr_b16 v[246:247], v166 offset:2368
	ds_read_b64_tr_b16 v[248:249], v166 offset:96
	ds_read_b64_tr_b16 v[250:251], v166 offset:2400
	s_waitcnt lgkmcnt(0)
	s_add_i32 s2, s42, -32
	v_add_u32_e32 v136, s2, v164
	v_med3_i32 v136, v136, 0, s14
	v_lshl_add_u32 v136, v136, 9, v162
	global_load_dwordx4 v[16:19], v136, s[86:87]
	s_add_i32 s2, s42, -24
	v_add_u32_e32 v135, s2, v164
	v_med3_i32 v135, v135, 0, s14
	v_lshl_add_u32 v135, v135, 9, v162
	global_load_dwordx4 v[20:23], v135, s[86:87]
	s_add_i32 s2, s42, -16
	v_add_u32_e32 v136, s2, v164
	v_med3_i32 v136, v136, 0, s14
	v_lshl_add_u32 v136, v136, 9, v162
	global_load_dwordx4 v[24:27], v136, s[86:87]
	s_add_i32 s2, s42, -8
	v_add_u32_e32 v135, s2, v164
	v_med3_i32 v135, v135, 0, s14
	v_lshl_add_u32 v135, v135, 9, v162
	global_load_dwordx4 v[28:31], v135, s[86:87]
	s_waitcnt vmcnt(8)
	ds_write_b128 v165, v[32:35]
	ds_write_b128 v165, v[36:39] offset:1152
	v_mfma_f32_16x16x32_bf16 v[204:207], v[236:239], v[124:127], v[204:207]
	v_mfma_f32_16x16x32_bf16 v[208:211], v[240:243], v[124:127], v[208:211]
	v_mfma_f32_16x16x32_bf16 v[212:215], v[244:247], v[124:127], v[212:215]
	v_mfma_f32_16x16x32_bf16 v[216:219], v[248:251], v[124:127], v[216:219]
	s_waitcnt lgkmcnt(0)
	ds_read_b64_tr_b16 v[236:237], v166
	ds_read_b64_tr_b16 v[238:239], v166 offset:2304
	ds_read_b64_tr_b16 v[240:241], v166 offset:32
	ds_read_b64_tr_b16 v[242:243], v166 offset:2336
	ds_read_b64_tr_b16 v[244:245], v166 offset:64
	ds_read_b64_tr_b16 v[246:247], v166 offset:2368
	ds_read_b64_tr_b16 v[248:249], v166 offset:96
	ds_read_b64_tr_b16 v[250:251], v166 offset:2400
	s_waitcnt lgkmcnt(0)
	s_add_i32 s2, s42, 0
	v_add_u32_e32 v136, s2, v164
	v_med3_i32 v136, v136, 0, s14
	v_lshl_add_u32 v136, v136, 9, v162
	global_load_dwordx4 v[32:35], v136, s[86:87]
	s_add_i32 s2, s42, 8
	v_add_u32_e32 v135, s2, v164
	v_med3_i32 v135, v135, 0, s14
	v_lshl_add_u32 v135, v135, 9, v162
	global_load_dwordx4 v[36:39], v135, s[86:87]
	s_add_i32 s2, s42, 16
	v_add_u32_e32 v136, s2, v164
	v_med3_i32 v136, v136, 0, s14
	v_lshl_add_u32 v136, v136, 9, v162
	global_load_dwordx4 v[40:43], v136, s[86:87]
	s_add_i32 s2, s42, 24
	v_add_u32_e32 v135, s2, v164
	v_med3_i32 v135, v135, 0, s14
	v_lshl_add_u32 v135, v135, 9, v162
	global_load_dwordx4 v[44:47], v135, s[86:87]
	v_mfma_f32_16x16x32_bf16 v[204:207], v[236:239], v[128:131], v[204:207]
	v_mfma_f32_16x16x32_bf16 v[208:211], v[240:243], v[128:131], v[208:211]
	v_mfma_f32_16x16x32_bf16 v[212:215], v[244:247], v[128:131], v[212:215]
	v_mfma_f32_16x16x32_bf16 v[216:219], v[248:251], v[128:131], v[216:219]
	s_add_i32 s2, s42, 32
	v_add_u32_e32 v136, s2, v164
	v_med3_i32 v136, v136, 0, s14
	v_lshl_add_u32 v136, v136, 9, v162
	global_load_dwordx4 v[120:123], v136, s[86:87]
	s_add_i32 s2, s42, 40
	v_add_u32_e32 v135, s2, v164
	v_med3_i32 v135, v135, 0, s14
	v_lshl_add_u32 v135, v135, 9, v162
	global_load_dwordx4 v[124:127], v135, s[86:87]
	s_add_i32 s2, s42, 48
	v_add_u32_e32 v136, s2, v164
	v_med3_i32 v136, v136, 0, s14
	v_lshl_add_u32 v136, v136, 9, v162
	global_load_dwordx4 v[192:195], v136, s[86:87]
	s_add_i32 s2, s42, 56
	v_add_u32_e32 v135, s2, v164
	v_med3_i32 v135, v135, 0, s14
	v_lshl_add_u32 v135, v135, 9, v162
	global_load_dwordx4 v[196:199], v135, s[86:87]
	s_and_b32 s2, s43, 3
	s_lshl_b32 s2, s2, s13
	s_lshr_b32 s3, s43, 2
	s_add_i32 s2, s2, s3
	s_lshl_b32 s2, s2, 7
	s_add_u32 s74, s22, s2
	s_addc_u32 s75, s23, 0
	s_add_i32 s2, s42, -64
	v_add_u32_e32 v137, s2, v164
	v_med3_i32 v137, v137, 0, s14
	v_lshl_add_u32 v137, v137, 9, v162
	global_load_dwordx4 v[64:67], v137, s[74:75]
	s_add_i32 s2, s42, -56
	v_add_u32_e32 v137, s2, v164
	v_med3_i32 v137, v137, 0, s14
	v_lshl_add_u32 v137, v137, 9, v162
	global_load_dwordx4 v[68:71], v137, s[74:75]
	s_add_i32 s2, s42, -48
	v_add_u32_e32 v137, s2, v164
	v_med3_i32 v137, v137, 0, s14
	v_lshl_add_u32 v137, v137, 9, v162
	global_load_dwordx4 v[72:75], v137, s[74:75]
	s_add_i32 s2, s42, -40
	v_add_u32_e32 v137, s2, v164
	v_med3_i32 v137, v137, 0, s14
	v_lshl_add_u32 v137, v137, 9, v162
	global_load_dwordx4 v[76:79], v137, s[74:75]
	s_and_b32 s2, s43, 3
	s_lshl_b32 s2, s2, s13
	s_lshr_b32 s3, s43, 2
	s_add_i32 s2, s2, s3
	s_lshl_b32 s2, s2, 7
	s_add_u32 s74, s22, s2
	s_addc_u32 s75, s23, 0
	s_add_i32 s2, s42, -32
	v_add_u32_e32 v137, s2, v164
	v_med3_i32 v137, v137, 0, s14
	v_lshl_add_u32 v137, v137, 9, v162
	global_load_dwordx4 v[80:83], v137, s[74:75]
	s_add_i32 s2, s42, -24
	v_add_u32_e32 v137, s2, v164
	v_med3_i32 v137, v137, 0, s14
	v_lshl_add_u32 v137, v137, 9, v162
	global_load_dwordx4 v[84:87], v137, s[74:75]
	s_add_i32 s2, s42, -16
	v_add_u32_e32 v137, s2, v164
	v_med3_i32 v137, v137, 0, s14
	v_lshl_add_u32 v137, v137, 9, v162
	global_load_dwordx4 v[88:91], v137, s[74:75]
	s_add_i32 s2, s42, -8
	v_add_u32_e32 v137, s2, v164
	v_med3_i32 v137, v137, 0, s14
	v_lshl_add_u32 v137, v137, 9, v162
	global_load_dwordx4 v[92:95], v137, s[74:75]
	s_and_b32 s2, s43, 3
	s_lshl_b32 s2, s2, s13
	s_lshr_b32 s3, s43, 2
	s_add_i32 s2, s2, s3
	s_lshl_b32 s2, s2, 7
	s_add_u32 s74, s22, s2
	s_addc_u32 s75, s23, 0
	s_add_i32 s2, s42, 0
	v_add_u32_e32 v137, s2, v164
	v_med3_i32 v137, v137, 0, s14
	v_lshl_add_u32 v137, v137, 9, v162
	global_load_dwordx4 v[96:99], v137, s[74:75]
	s_add_i32 s2, s42, 8
	v_add_u32_e32 v137, s2, v164
	v_med3_i32 v137, v137, 0, s14
	v_lshl_add_u32 v137, v137, 9, v162
	global_load_dwordx4 v[100:103], v137, s[74:75]
	s_add_i32 s2, s42, 16
	v_add_u32_e32 v137, s2, v164
	v_med3_i32 v137, v137, 0, s14
	v_lshl_add_u32 v137, v137, 9, v162
	global_load_dwordx4 v[104:107], v137, s[74:75]
	s_add_i32 s2, s42, 24
	v_add_u32_e32 v137, s2, v164
	v_med3_i32 v137, v137, 0, s14
	v_lshl_add_u32 v137, v137, 9, v162
	global_load_dwordx4 v[108:111], v137, s[74:75]
	s_waitcnt lgkmcnt(0)
	s_barrier
	ds_read_b128 v[236:239], v173 offset:0
	ds_read_b128 v[240:243], v173 offset:64
	ds_read_b128 v[244:247], v173 offset:128
	ds_read_b128 v[248:251], v173 offset:192
	ds_read_b32 v142, v174 offset:0
	s_waitcnt lgkmcnt(0)
	v_add_f32_e32 v204, v236, v204
	v_add_f32_e32 v205, v237, v205
	v_add_f32_e32 v206, v238, v206
	v_add_f32_e32 v207, v239, v207
	v_add_f32_e32 v208, v240, v208
	v_add_f32_e32 v209, v241, v209
	v_add_f32_e32 v210, v242, v210
	v_add_f32_e32 v211, v243, v211
	v_add_f32_e32 v212, v244, v212
	v_add_f32_e32 v213, v245, v213
	v_add_f32_e32 v214, v246, v214
	v_add_f32_e32 v215, v247, v215
	v_add_f32_e32 v216, v248, v216
	v_add_f32_e32 v217, v249, v217
	v_add_f32_e32 v218, v250, v218
	v_add_f32_e32 v219, v251, v219
	v_add_f32_e32 v132, v142, v132
	ds_write_b128 v173, v[204:207] offset:0
	ds_write_b128 v173, v[208:211] offset:64
	ds_write_b128 v173, v[212:215] offset:128
	ds_write_b128 v173, v[216:219] offset:192
	ds_write_b32 v174, v132 offset:0
	s_mov_b32 s40, s42
	s_mov_b32 s41, s43
	v_mov_b32_e32 v173, v176
	v_mov_b32_e32 v174, v177
	s_lshr_b32 s44, s33, 4
	s_add_i32 s45, s10, s8
	s_cmp_lt_u32 s45, 0x800
	s_cbranch_scc1 .Latt_newunit
	s_mov_b32 s37, 1
	s_branch .Latt_ud_done
